# LDS-staged GDN+mLSTM (mLSTM gate recurrence as per-chunk scan), retention decay folded into running scale, GDN prio
# speedup vs baseline: 1.1314x; 1.0165x over previous
.Lret2_item:
	s_lshr_b32 s0, s23, 5
	s_and_b32 s1, s23, 31
	s_lshr_b32 s2, s0, 2
	s_and_b32 s3, s0, 3
	s_lshl_b32 s4, s1, 4
	v_lshl_add_u32 v46, v5, 2, s4
	s_and_b32 s4, s1, 3
	s_lshl_b32 s4, s4, 5
	s_add_u32 s4, s4, 128
	v_lshl_add_u32 v3, v5, 3, s4
	s_lshl_b32 s4, s3, 8
	s_add_u32 s4, s4, 1024
	v_lshl_add_u32 v32, v198, 2, s4
	s_add_u32 s4, s4, 4096
	v_lshl_add_u32 v33, v198, 2, s4
	s_lshl_b32 s4, s3, 9
	s_and_b32 s5, s1, 28
	s_lshl_b32 s5, s5, 4
	s_add_u32 s4, s4, s5
	s_add_u32 s4, s4, 2048
	v_min_u32_e32 v42, 31, v198
	v_lshl_add_u32 v34, v42, 2, s4
	v_cmp_lt_u32_e32 vcc, 15, v198
	v_add_u32_e32 v44, 4032, v34
	s_nop 1
	v_cndmask_b32_e32 v34, v34, v44, vcc
	v_readlane_b32 s5, v255, 15
	s_mul_i32 s4, s2, 0x1800000
	s_mul_i32 s1, s5, 0x3000
	s_add_u32 s4, s4, s1
	s_add_u32 s4, s4, 0x3bc0400
	s_add_u32 s10, s8, s4
	s_addc_u32 s11, s9, 0
	s_lshl_b32 s4, s2, 22
	s_lshl_b32 s1, s5, 11
	s_add_u32 s4, s4, s1
	s_lshl_b32 s1, s3, 9
	s_add_u32 s4, s4, s1
	s_add_u32 s4, s4, 0xfd40400
	s_add_u32 s12, s8, s4
	s_addc_u32 s13, s9, 0
	s_lshl_b32 s4, s2, 23
	s_add_u32 s4, s4, s1
	s_add_u32 s4, s4, 333188096
	s_add_u32 s14, s8, s4
	s_addc_u32 s15, s9, 0
	s_lshr_b32 s4, 0x80000, s3
	s_sub_u32 s4, 0x3f800000, s4
	v_mov_b32_e32 v43, s4
	v_rcp_f32_e32 v42, v43
	v_mov_b32_e32 v40, 1.0
	v_mov_b32_e32 v41, 1.0
	s_movk_i32 s20, 256
	s_movk_i32 s21, 24832
	s_mov_b32 s22, 49408
	v_add_u32_e32 v26, s20, v29
	v_add_u32_e32 v27, s20, v30
	v_add_u32_e32 v28, s20, v31
	global_load_dword v84, v32, s[10:11]
	global_load_dword v85, v32, s[10:11] offset:-1024
	global_load_dword v86, v33, s[10:11]
	global_load_dword v87, v33, s[10:11] offset:-1024
	global_load_dword v88, v34, s[10:11]
	global_load_dword v90, v35, s[12:13]
	global_load_dword v91, v35, s[12:13] offset:4
	s_add_u32 s10, s10, 0x18000
	s_addc_u32 s11, s11, 0
	s_add_u32 s12, s12, 0x4000
	s_addc_u32 s13, s13, 0
	s_waitcnt vmcnt(0)
	v_lshlrev_b32_e32 v108, 16, v84
	v_lshlrev_b32_e32 v109, 16, v85
	v_and_b32_e32 v110, s17, v84
	v_and_b32_e32 v111, s17, v85
	v_lshlrev_b32_e32 v112, 16, v86
	v_lshlrev_b32_e32 v113, 16, v87
	v_and_b32_e32 v114, s17, v86
	v_and_b32_e32 v115, s17, v87
	v_lshlrev_b32_e32 v116, 16, v88
	v_and_b32_e32 v117, s17, v88
	ds_write_b128 v26, v[108:111] offset:0
	ds_write_b128 v26, v[112:115] offset:8192
	ds_write_b64 v27, v[90:91]
	ds_write_b64 v28, v[116:117]
	v_add_u32_e32 v26, s21, v29
	v_add_u32_e32 v27, s21, v30
	v_add_u32_e32 v28, s21, v31
	global_load_dword v84, v32, s[10:11]
	global_load_dword v85, v32, s[10:11] offset:-1024
	global_load_dword v86, v33, s[10:11]
	global_load_dword v87, v33, s[10:11] offset:-1024
	global_load_dword v88, v34, s[10:11]
	global_load_dword v90, v35, s[12:13]
	global_load_dword v91, v35, s[12:13] offset:4
	s_add_u32 s10, s10, 0x18000
	s_addc_u32 s11, s11, 0
	s_add_u32 s12, s12, 0x4000
	s_addc_u32 s13, s13, 0
	s_waitcnt vmcnt(0)
	v_lshlrev_b32_e32 v108, 16, v84
	v_lshlrev_b32_e32 v109, 16, v85
	v_and_b32_e32 v110, s17, v84
	v_and_b32_e32 v111, s17, v85
	v_lshlrev_b32_e32 v112, 16, v86
	v_lshlrev_b32_e32 v113, 16, v87
	v_and_b32_e32 v114, s17, v86
	v_and_b32_e32 v115, s17, v87
	v_lshlrev_b32_e32 v116, 16, v88
	v_and_b32_e32 v117, s17, v88
	ds_write_b128 v26, v[108:111] offset:0
	ds_write_b128 v26, v[112:115] offset:8192
	ds_write_b64 v27, v[90:91]
	ds_write_b64 v28, v[116:117]
	v_add_u32_e32 v26, s22, v29
	v_add_u32_e32 v27, s22, v30
	v_add_u32_e32 v28, s22, v31
	v_add_u32_e32 v22, s20, v2
	v_add_u32_e32 v23, s20, v3
	v_add_u32_e32 v24, s21, v2
	v_add_u32_e32 v25, s21, v3
	v_mov_b32_e32 v6, 0
	v_mov_b32_e32 v7, 0
	v_mov_b32_e32 v8, 0
	v_mov_b32_e32 v9, 0
	v_mov_b32_e32 v10, 0
	v_mov_b32_e32 v11, 0
	v_mov_b32_e32 v12, 0
	v_mov_b32_e32 v13, 0
	v_mov_b32_e32 v14, 0
	v_mov_b32_e32 v15, 0
	v_mov_b32_e32 v16, 0
	v_mov_b32_e32 v17, 0
	v_mov_b32_e32 v18, 0
	v_mov_b32_e32 v19, 0
	v_mov_b32_e32 v20, 0
	v_mov_b32_e32 v21, 0
	s_mov_b32 s16, 0
	s_mov_b32 s2, 0x10001
	s_mov_b32 s3, 0x10001
	s_waitcnt vmcnt(0) lgkmcnt(0)
	s_barrier
	ds_read_b128 v[48:51], v22 offset:8192
	ds_read_b128 v[52:55], v22 offset:8448
	ds_read_b128 v[56:59], v22 offset:8704
	ds_read_b128 v[60:63], v22 offset:8960
	ds_read_b64 v[64:65], v23 offset:20480
.Lret2_loop:
	global_load_dword v84, v32, s[10:11]
	global_load_dword v85, v32, s[10:11] offset:-1024
	global_load_dword v86, v33, s[10:11]
	global_load_dword v87, v33, s[10:11] offset:-1024
	global_load_dword v88, v34, s[10:11]
	global_load_dword v90, v35, s[12:13]
	global_load_dword v91, v35, s[12:13] offset:4
	s_add_u32 s10, s10, 0x18000
	s_addc_u32 s11, s11, 0
	s_add_u32 s12, s12, 0x4000
	s_addc_u32 s13, s13, 0
	ds_read_b128 v[66:69], v22 offset:9216
	ds_read_b128 v[70:73], v22 offset:9472
	ds_read_b128 v[74:77], v22 offset:9728
	ds_read_b128 v[78:81], v22 offset:9984
	ds_read_b64 v[82:83], v23 offset:20736
	s_waitcnt lgkmcnt(5)
	v_pk_mul_f32 v[40:41], v[40:41], v[42:43]
	v_rcp_f32_e32 v40, v41
	s_nop 0
	v_pk_mul_f32 v[44:45], v[64:65], v[40:41] op_sel_hi:[1,0]
	v_pk_fma_f32 v[6:7], v[44:45], v[48:49], v[6:7] op_sel_hi:[1,0,1]
	v_pk_mul_f32 v[38:39], v[6:7], v[48:49] op_sel:[0,1] op_sel_hi:[1,1]
	v_pk_fma_f32 v[8:9], v[44:45], v[50:51], v[8:9] op_sel_hi:[1,0,1]
	v_pk_fma_f32 v[38:39], v[8:9], v[50:51], v[38:39] op_sel:[0,1,0] op_sel_hi:[1,1,1]
	v_pk_fma_f32 v[10:11], v[44:45], v[52:53], v[10:11] op_sel_hi:[1,0,1]
	v_pk_fma_f32 v[38:39], v[10:11], v[52:53], v[38:39] op_sel:[0,1,0] op_sel_hi:[1,1,1]
	v_pk_fma_f32 v[12:13], v[44:45], v[54:55], v[12:13] op_sel_hi:[1,0,1]
	v_pk_fma_f32 v[38:39], v[12:13], v[54:55], v[38:39] op_sel:[0,1,0] op_sel_hi:[1,1,1]
	v_pk_fma_f32 v[14:15], v[44:45], v[56:57], v[14:15] op_sel_hi:[1,0,1]
	v_pk_fma_f32 v[38:39], v[14:15], v[56:57], v[38:39] op_sel:[0,1,0] op_sel_hi:[1,1,1]
	v_pk_fma_f32 v[16:17], v[44:45], v[58:59], v[16:17] op_sel_hi:[1,0,1]
	v_pk_fma_f32 v[38:39], v[16:17], v[58:59], v[38:39] op_sel:[0,1,0] op_sel_hi:[1,1,1]
	v_pk_fma_f32 v[18:19], v[44:45], v[60:61], v[18:19] op_sel_hi:[1,0,1]
	v_pk_fma_f32 v[38:39], v[18:19], v[60:61], v[38:39] op_sel:[0,1,0] op_sel_hi:[1,1,1]
	v_pk_fma_f32 v[20:21], v[44:45], v[62:63], v[20:21] op_sel_hi:[1,0,1]
	v_pk_fma_f32 v[38:39], v[20:21], v[62:63], v[38:39] op_sel:[0,1,0] op_sel_hi:[1,1,1]
	s_add_u32 s14, s14, 0x1000
	s_addc_u32 s15, s15, 0
	v_add_f32_dpp v38, v38, v38 quad_perm:[1,0,3,2] row_mask:0xf bank_mask:0xf bound_ctrl:1
	v_add_f32_dpp v39, v39, v39 quad_perm:[1,0,3,2] row_mask:0xf bank_mask:0xf bound_ctrl:1
	s_nop 0
	v_add_f32_dpp v38, v38, v38 quad_perm:[2,3,0,1] row_mask:0xf bank_mask:0xf bound_ctrl:1
	v_add_f32_dpp v39, v39, v39 quad_perm:[2,3,0,1] row_mask:0xf bank_mask:0xf bound_ctrl:1
	s_nop 0
	v_add_f32_dpp v38, v38, v38 row_half_mirror row_mask:0xf bank_mask:0xf bound_ctrl:1
	v_add_f32_dpp v39, v39, v39 row_half_mirror row_mask:0xf bank_mask:0xf bound_ctrl:1
	s_nop 0
	v_add_f32_dpp v38, v38, v38 row_mirror row_mask:0xf bank_mask:0xf bound_ctrl:1
	v_add_f32_dpp v39, v39, v39 row_mirror row_mask:0xf bank_mask:0xf bound_ctrl:1
	v_pk_mul_f32 v[38:39], v[38:39], v[40:41] op_sel:[0,1] op_sel_hi:[1,1]
	v_cvt_pk_bf16_f32 v47, v38, v39
	s_mov_b64 exec, s[2:3]
	global_store_dword v46, v47, s[14:15] offset:-4096
	s_mov_b64 exec, -1
	ds_read_b128 v[48:51], v22 offset:10240
	ds_read_b128 v[52:55], v22 offset:10496
	ds_read_b128 v[56:59], v22 offset:10752
	ds_read_b128 v[60:63], v22 offset:11008
	ds_read_b64 v[64:65], v23 offset:20992
	s_waitcnt lgkmcnt(5)
	v_pk_mul_f32 v[40:41], v[40:41], v[42:43]
	v_pk_mul_f32 v[44:45], v[82:83], v[40:41] op_sel_hi:[1,0]
	v_pk_fma_f32 v[6:7], v[44:45], v[66:67], v[6:7] op_sel_hi:[1,0,1]
	v_pk_mul_f32 v[38:39], v[6:7], v[66:67] op_sel:[0,1] op_sel_hi:[1,1]
	v_pk_fma_f32 v[8:9], v[44:45], v[68:69], v[8:9] op_sel_hi:[1,0,1]
	v_pk_fma_f32 v[38:39], v[8:9], v[68:69], v[38:39] op_sel:[0,1,0] op_sel_hi:[1,1,1]
	v_pk_fma_f32 v[10:11], v[44:45], v[70:71], v[10:11] op_sel_hi:[1,0,1]
	v_pk_fma_f32 v[38:39], v[10:11], v[70:71], v[38:39] op_sel:[0,1,0] op_sel_hi:[1,1,1]
	v_pk_fma_f32 v[12:13], v[44:45], v[72:73], v[12:13] op_sel_hi:[1,0,1]
	v_pk_fma_f32 v[38:39], v[12:13], v[72:73], v[38:39] op_sel:[0,1,0] op_sel_hi:[1,1,1]
	v_pk_fma_f32 v[14:15], v[44:45], v[74:75], v[14:15] op_sel_hi:[1,0,1]
	v_pk_fma_f32 v[38:39], v[14:15], v[74:75], v[38:39] op_sel:[0,1,0] op_sel_hi:[1,1,1]
	v_pk_fma_f32 v[16:17], v[44:45], v[76:77], v[16:17] op_sel_hi:[1,0,1]
	v_pk_fma_f32 v[38:39], v[16:17], v[76:77], v[38:39] op_sel:[0,1,0] op_sel_hi:[1,1,1]
	v_pk_fma_f32 v[18:19], v[44:45], v[78:79], v[18:19] op_sel_hi:[1,0,1]
	v_pk_fma_f32 v[38:39], v[18:19], v[78:79], v[38:39] op_sel:[0,1,0] op_sel_hi:[1,1,1]
	v_pk_fma_f32 v[20:21], v[44:45], v[80:81], v[20:21] op_sel_hi:[1,0,1]
	v_pk_fma_f32 v[38:39], v[20:21], v[80:81], v[38:39] op_sel:[0,1,0] op_sel_hi:[1,1,1]
	s_add_u32 s14, s14, 0x1000
	s_addc_u32 s15, s15, 0
	v_add_f32_dpp v38, v38, v38 quad_perm:[1,0,3,2] row_mask:0xf bank_mask:0xf bound_ctrl:1
	v_add_f32_dpp v39, v39, v39 quad_perm:[1,0,3,2] row_mask:0xf bank_mask:0xf bound_ctrl:1
	s_nop 0
	v_add_f32_dpp v38, v38, v38 quad_perm:[2,3,0,1] row_mask:0xf bank_mask:0xf bound_ctrl:1
	v_add_f32_dpp v39, v39, v39 quad_perm:[2,3,0,1] row_mask:0xf bank_mask:0xf bound_ctrl:1
	s_nop 0
	v_add_f32_dpp v38, v38, v38 row_half_mirror row_mask:0xf bank_mask:0xf bound_ctrl:1
	v_add_f32_dpp v39, v39, v39 row_half_mirror row_mask:0xf bank_mask:0xf bound_ctrl:1
	s_nop 0
	v_add_f32_dpp v38, v38, v38 row_mirror row_mask:0xf bank_mask:0xf bound_ctrl:1
	v_add_f32_dpp v39, v39, v39 row_mirror row_mask:0xf bank_mask:0xf bound_ctrl:1
	v_pk_mul_f32 v[38:39], v[38:39], v[40:41] op_sel:[0,1] op_sel_hi:[1,1]
	v_cvt_pk_bf16_f32 v47, v38, v39
	s_mov_b64 exec, s[2:3]
	global_store_dword v46, v47, s[14:15] offset:-4096
	s_mov_b64 exec, -1
	ds_read_b128 v[66:69], v22 offset:11264
	ds_read_b128 v[70:73], v22 offset:11520
	ds_read_b128 v[74:77], v22 offset:11776
	ds_read_b128 v[78:81], v22 offset:12032
	ds_read_b64 v[82:83], v23 offset:21248
	s_waitcnt lgkmcnt(5)
	v_pk_mul_f32 v[40:41], v[40:41], v[42:43]
	v_pk_mul_f32 v[44:45], v[64:65], v[40:41] op_sel_hi:[1,0]
	v_pk_fma_f32 v[6:7], v[44:45], v[48:49], v[6:7] op_sel_hi:[1,0,1]
	v_pk_mul_f32 v[38:39], v[6:7], v[48:49] op_sel:[0,1] op_sel_hi:[1,1]
	v_pk_fma_f32 v[8:9], v[44:45], v[50:51], v[8:9] op_sel_hi:[1,0,1]
	v_pk_fma_f32 v[38:39], v[8:9], v[50:51], v[38:39] op_sel:[0,1,0] op_sel_hi:[1,1,1]
	v_pk_fma_f32 v[10:11], v[44:45], v[52:53], v[10:11] op_sel_hi:[1,0,1]
	v_pk_fma_f32 v[38:39], v[10:11], v[52:53], v[38:39] op_sel:[0,1,0] op_sel_hi:[1,1,1]
	v_pk_fma_f32 v[12:13], v[44:45], v[54:55], v[12:13] op_sel_hi:[1,0,1]
	v_pk_fma_f32 v[38:39], v[12:13], v[54:55], v[38:39] op_sel:[0,1,0] op_sel_hi:[1,1,1]
	v_pk_fma_f32 v[14:15], v[44:45], v[56:57], v[14:15] op_sel_hi:[1,0,1]
	v_pk_fma_f32 v[38:39], v[14:15], v[56:57], v[38:39] op_sel:[0,1,0] op_sel_hi:[1,1,1]
	v_pk_fma_f32 v[16:17], v[44:45], v[58:59], v[16:17] op_sel_hi:[1,0,1]
	v_pk_fma_f32 v[38:39], v[16:17], v[58:59], v[38:39] op_sel:[0,1,0] op_sel_hi:[1,1,1]
	v_pk_fma_f32 v[18:19], v[44:45], v[60:61], v[18:19] op_sel_hi:[1,0,1]
	v_pk_fma_f32 v[38:39], v[18:19], v[60:61], v[38:39] op_sel:[0,1,0] op_sel_hi:[1,1,1]
	v_pk_fma_f32 v[20:21], v[44:45], v[62:63], v[20:21] op_sel_hi:[1,0,1]
	v_pk_fma_f32 v[38:39], v[20:21], v[62:63], v[38:39] op_sel:[0,1,0] op_sel_hi:[1,1,1]
	s_add_u32 s14, s14, 0x1000
	s_addc_u32 s15, s15, 0
	v_add_f32_dpp v38, v38, v38 quad_perm:[1,0,3,2] row_mask:0xf bank_mask:0xf bound_ctrl:1
	v_add_f32_dpp v39, v39, v39 quad_perm:[1,0,3,2] row_mask:0xf bank_mask:0xf bound_ctrl:1
	s_nop 0
	v_add_f32_dpp v38, v38, v38 quad_perm:[2,3,0,1] row_mask:0xf bank_mask:0xf bound_ctrl:1
	v_add_f32_dpp v39, v39, v39 quad_perm:[2,3,0,1] row_mask:0xf bank_mask:0xf bound_ctrl:1
	s_nop 0
	v_add_f32_dpp v38, v38, v38 row_half_mirror row_mask:0xf bank_mask:0xf bound_ctrl:1
	v_add_f32_dpp v39, v39, v39 row_half_mirror row_mask:0xf bank_mask:0xf bound_ctrl:1
	s_nop 0
	v_add_f32_dpp v38, v38, v38 row_mirror row_mask:0xf bank_mask:0xf bound_ctrl:1
	v_add_f32_dpp v39, v39, v39 row_mirror row_mask:0xf bank_mask:0xf bound_ctrl:1
	v_pk_mul_f32 v[38:39], v[38:39], v[40:41] op_sel:[0,1] op_sel_hi:[1,1]
	v_cvt_pk_bf16_f32 v47, v38, v39
	s_mov_b64 exec, s[2:3]
	global_store_dword v46, v47, s[14:15] offset:-4096
	s_mov_b64 exec, -1
	ds_read_b128 v[48:51], v22 offset:12288
	ds_read_b128 v[52:55], v22 offset:12544
	ds_read_b128 v[56:59], v22 offset:12800
	ds_read_b128 v[60:63], v22 offset:13056
	ds_read_b64 v[64:65], v23 offset:21504
	s_waitcnt lgkmcnt(5)
	v_pk_mul_f32 v[40:41], v[40:41], v[42:43]
	v_pk_mul_f32 v[44:45], v[82:83], v[40:41] op_sel_hi:[1,0]
	v_pk_fma_f32 v[6:7], v[44:45], v[66:67], v[6:7] op_sel_hi:[1,0,1]
	v_pk_mul_f32 v[38:39], v[6:7], v[66:67] op_sel:[0,1] op_sel_hi:[1,1]
	v_pk_fma_f32 v[8:9], v[44:45], v[68:69], v[8:9] op_sel_hi:[1,0,1]
	v_pk_fma_f32 v[38:39], v[8:9], v[68:69], v[38:39] op_sel:[0,1,0] op_sel_hi:[1,1,1]
	v_pk_fma_f32 v[10:11], v[44:45], v[70:71], v[10:11] op_sel_hi:[1,0,1]
	v_pk_fma_f32 v[38:39], v[10:11], v[70:71], v[38:39] op_sel:[0,1,0] op_sel_hi:[1,1,1]
	v_pk_fma_f32 v[12:13], v[44:45], v[72:73], v[12:13] op_sel_hi:[1,0,1]
	v_pk_fma_f32 v[38:39], v[12:13], v[72:73], v[38:39] op_sel:[0,1,0] op_sel_hi:[1,1,1]
	v_pk_fma_f32 v[14:15], v[44:45], v[74:75], v[14:15] op_sel_hi:[1,0,1]
	v_pk_fma_f32 v[38:39], v[14:15], v[74:75], v[38:39] op_sel:[0,1,0] op_sel_hi:[1,1,1]
	v_pk_fma_f32 v[16:17], v[44:45], v[76:77], v[16:17] op_sel_hi:[1,0,1]
	v_pk_fma_f32 v[38:39], v[16:17], v[76:77], v[38:39] op_sel:[0,1,0] op_sel_hi:[1,1,1]
	v_pk_fma_f32 v[18:19], v[44:45], v[78:79], v[18:19] op_sel_hi:[1,0,1]
	v_pk_fma_f32 v[38:39], v[18:19], v[78:79], v[38:39] op_sel:[0,1,0] op_sel_hi:[1,1,1]
	v_pk_fma_f32 v[20:21], v[44:45], v[80:81], v[20:21] op_sel_hi:[1,0,1]
	v_pk_fma_f32 v[38:39], v[20:21], v[80:81], v[38:39] op_sel:[0,1,0] op_sel_hi:[1,1,1]
	s_add_u32 s14, s14, 0x1000
	s_addc_u32 s15, s15, 0
	v_add_f32_dpp v38, v38, v38 quad_perm:[1,0,3,2] row_mask:0xf bank_mask:0xf bound_ctrl:1
	v_add_f32_dpp v39, v39, v39 quad_perm:[1,0,3,2] row_mask:0xf bank_mask:0xf bound_ctrl:1
	s_nop 0
	v_add_f32_dpp v38, v38, v38 quad_perm:[2,3,0,1] row_mask:0xf bank_mask:0xf bound_ctrl:1
	v_add_f32_dpp v39, v39, v39 quad_perm:[2,3,0,1] row_mask:0xf bank_mask:0xf bound_ctrl:1
	s_nop 0
	v_add_f32_dpp v38, v38, v38 row_half_mirror row_mask:0xf bank_mask:0xf bound_ctrl:1
	v_add_f32_dpp v39, v39, v39 row_half_mirror row_mask:0xf bank_mask:0xf bound_ctrl:1
	s_nop 0
	v_add_f32_dpp v38, v38, v38 row_mirror row_mask:0xf bank_mask:0xf bound_ctrl:1
	v_add_f32_dpp v39, v39, v39 row_mirror row_mask:0xf bank_mask:0xf bound_ctrl:1
	v_pk_mul_f32 v[38:39], v[38:39], v[40:41] op_sel:[0,1] op_sel_hi:[1,1]
	v_cvt_pk_bf16_f32 v47, v38, v39
	s_mov_b64 exec, s[2:3]
	global_store_dword v46, v47, s[14:15] offset:-4096
	s_mov_b64 exec, -1
	ds_read_b128 v[66:69], v22 offset:13312
	ds_read_b128 v[70:73], v22 offset:13568
	ds_read_b128 v[74:77], v22 offset:13824
	ds_read_b128 v[78:81], v22 offset:14080
	ds_read_b64 v[82:83], v23 offset:21760
	s_waitcnt lgkmcnt(5)
	v_pk_mul_f32 v[40:41], v[40:41], v[42:43]
	v_pk_mul_f32 v[44:45], v[64:65], v[40:41] op_sel_hi:[1,0]
	v_pk_fma_f32 v[6:7], v[44:45], v[48:49], v[6:7] op_sel_hi:[1,0,1]
	v_pk_mul_f32 v[38:39], v[6:7], v[48:49] op_sel:[0,1] op_sel_hi:[1,1]
	v_pk_fma_f32 v[8:9], v[44:45], v[50:51], v[8:9] op_sel_hi:[1,0,1]
	v_pk_fma_f32 v[38:39], v[8:9], v[50:51], v[38:39] op_sel:[0,1,0] op_sel_hi:[1,1,1]
	v_pk_fma_f32 v[10:11], v[44:45], v[52:53], v[10:11] op_sel_hi:[1,0,1]
	v_pk_fma_f32 v[38:39], v[10:11], v[52:53], v[38:39] op_sel:[0,1,0] op_sel_hi:[1,1,1]
	v_pk_fma_f32 v[12:13], v[44:45], v[54:55], v[12:13] op_sel_hi:[1,0,1]
	v_pk_fma_f32 v[38:39], v[12:13], v[54:55], v[38:39] op_sel:[0,1,0] op_sel_hi:[1,1,1]
	v_pk_fma_f32 v[14:15], v[44:45], v[56:57], v[14:15] op_sel_hi:[1,0,1]
	v_pk_fma_f32 v[38:39], v[14:15], v[56:57], v[38:39] op_sel:[0,1,0] op_sel_hi:[1,1,1]
	v_pk_fma_f32 v[16:17], v[44:45], v[58:59], v[16:17] op_sel_hi:[1,0,1]
	v_pk_fma_f32 v[38:39], v[16:17], v[58:59], v[38:39] op_sel:[0,1,0] op_sel_hi:[1,1,1]
	v_pk_fma_f32 v[18:19], v[44:45], v[60:61], v[18:19] op_sel_hi:[1,0,1]
	v_pk_fma_f32 v[38:39], v[18:19], v[60:61], v[38:39] op_sel:[0,1,0] op_sel_hi:[1,1,1]
	v_pk_fma_f32 v[20:21], v[44:45], v[62:63], v[20:21] op_sel_hi:[1,0,1]
	v_pk_fma_f32 v[38:39], v[20:21], v[62:63], v[38:39] op_sel:[0,1,0] op_sel_hi:[1,1,1]
	s_add_u32 s14, s14, 0x1000
	s_addc_u32 s15, s15, 0
	v_add_f32_dpp v38, v38, v38 quad_perm:[1,0,3,2] row_mask:0xf bank_mask:0xf bound_ctrl:1
	v_add_f32_dpp v39, v39, v39 quad_perm:[1,0,3,2] row_mask:0xf bank_mask:0xf bound_ctrl:1
	s_nop 0
	v_add_f32_dpp v38, v38, v38 quad_perm:[2,3,0,1] row_mask:0xf bank_mask:0xf bound_ctrl:1
	v_add_f32_dpp v39, v39, v39 quad_perm:[2,3,0,1] row_mask:0xf bank_mask:0xf bound_ctrl:1
	s_nop 0
	v_add_f32_dpp v38, v38, v38 row_half_mirror row_mask:0xf bank_mask:0xf bound_ctrl:1
	v_add_f32_dpp v39, v39, v39 row_half_mirror row_mask:0xf bank_mask:0xf bound_ctrl:1
	s_nop 0
	v_add_f32_dpp v38, v38, v38 row_mirror row_mask:0xf bank_mask:0xf bound_ctrl:1
	v_add_f32_dpp v39, v39, v39 row_mirror row_mask:0xf bank_mask:0xf bound_ctrl:1
	v_pk_mul_f32 v[38:39], v[38:39], v[40:41] op_sel:[0,1] op_sel_hi:[1,1]
	v_cvt_pk_bf16_f32 v47, v38, v39
	s_mov_b64 exec, s[2:3]
	global_store_dword v46, v47, s[14:15] offset:-4096
	s_mov_b64 exec, -1
	ds_read_b128 v[48:51], v22 offset:14336
	ds_read_b128 v[52:55], v22 offset:14592
	ds_read_b128 v[56:59], v22 offset:14848
	ds_read_b128 v[60:63], v22 offset:15104
	ds_read_b64 v[64:65], v23 offset:22016
	s_waitcnt lgkmcnt(5)
	v_pk_mul_f32 v[40:41], v[40:41], v[42:43]
	v_pk_mul_f32 v[44:45], v[82:83], v[40:41] op_sel_hi:[1,0]
	v_pk_fma_f32 v[6:7], v[44:45], v[66:67], v[6:7] op_sel_hi:[1,0,1]
	v_pk_mul_f32 v[38:39], v[6:7], v[66:67] op_sel:[0,1] op_sel_hi:[1,1]
	v_pk_fma_f32 v[8:9], v[44:45], v[68:69], v[8:9] op_sel_hi:[1,0,1]
	v_pk_fma_f32 v[38:39], v[8:9], v[68:69], v[38:39] op_sel:[0,1,0] op_sel_hi:[1,1,1]
	v_pk_fma_f32 v[10:11], v[44:45], v[70:71], v[10:11] op_sel_hi:[1,0,1]
	v_pk_fma_f32 v[38:39], v[10:11], v[70:71], v[38:39] op_sel:[0,1,0] op_sel_hi:[1,1,1]
	v_pk_fma_f32 v[12:13], v[44:45], v[72:73], v[12:13] op_sel_hi:[1,0,1]
	v_pk_fma_f32 v[38:39], v[12:13], v[72:73], v[38:39] op_sel:[0,1,0] op_sel_hi:[1,1,1]
	v_pk_fma_f32 v[14:15], v[44:45], v[74:75], v[14:15] op_sel_hi:[1,0,1]
	v_pk_fma_f32 v[38:39], v[14:15], v[74:75], v[38:39] op_sel:[0,1,0] op_sel_hi:[1,1,1]
	v_pk_fma_f32 v[16:17], v[44:45], v[76:77], v[16:17] op_sel_hi:[1,0,1]
	v_pk_fma_f32 v[38:39], v[16:17], v[76:77], v[38:39] op_sel:[0,1,0] op_sel_hi:[1,1,1]
	v_pk_fma_f32 v[18:19], v[44:45], v[78:79], v[18:19] op_sel_hi:[1,0,1]
	v_pk_fma_f32 v[38:39], v[18:19], v[78:79], v[38:39] op_sel:[0,1,0] op_sel_hi:[1,1,1]
	v_pk_fma_f32 v[20:21], v[44:45], v[80:81], v[20:21] op_sel_hi:[1,0,1]
	v_pk_fma_f32 v[38:39], v[20:21], v[80:81], v[38:39] op_sel:[0,1,0] op_sel_hi:[1,1,1]
	s_add_u32 s14, s14, 0x1000
	s_addc_u32 s15, s15, 0
	v_add_f32_dpp v38, v38, v38 quad_perm:[1,0,3,2] row_mask:0xf bank_mask:0xf bound_ctrl:1
	v_add_f32_dpp v39, v39, v39 quad_perm:[1,0,3,2] row_mask:0xf bank_mask:0xf bound_ctrl:1
	s_nop 0
	v_add_f32_dpp v38, v38, v38 quad_perm:[2,3,0,1] row_mask:0xf bank_mask:0xf bound_ctrl:1
	v_add_f32_dpp v39, v39, v39 quad_perm:[2,3,0,1] row_mask:0xf bank_mask:0xf bound_ctrl:1
	s_nop 0
	v_add_f32_dpp v38, v38, v38 row_half_mirror row_mask:0xf bank_mask:0xf bound_ctrl:1
	v_add_f32_dpp v39, v39, v39 row_half_mirror row_mask:0xf bank_mask:0xf bound_ctrl:1
	s_nop 0
	v_add_f32_dpp v38, v38, v38 row_mirror row_mask:0xf bank_mask:0xf bound_ctrl:1
	v_add_f32_dpp v39, v39, v39 row_mirror row_mask:0xf bank_mask:0xf bound_ctrl:1
	v_pk_mul_f32 v[38:39], v[38:39], v[40:41] op_sel:[0,1] op_sel_hi:[1,1]
	v_cvt_pk_bf16_f32 v47, v38, v39
	s_mov_b64 exec, s[2:3]
	global_store_dword v46, v47, s[14:15] offset:-4096
	s_mov_b64 exec, -1
	ds_read_b128 v[66:69], v22 offset:15360
	ds_read_b128 v[70:73], v22 offset:15616
	ds_read_b128 v[74:77], v22 offset:15872
	ds_read_b128 v[78:81], v22 offset:16128
	ds_read_b64 v[82:83], v23 offset:22272
	s_waitcnt lgkmcnt(5)
	v_pk_mul_f32 v[40:41], v[40:41], v[42:43]
	v_pk_mul_f32 v[44:45], v[64:65], v[40:41] op_sel_hi:[1,0]
	v_pk_fma_f32 v[6:7], v[44:45], v[48:49], v[6:7] op_sel_hi:[1,0,1]
	v_pk_mul_f32 v[38:39], v[6:7], v[48:49] op_sel:[0,1] op_sel_hi:[1,1]
	v_pk_fma_f32 v[8:9], v[44:45], v[50:51], v[8:9] op_sel_hi:[1,0,1]
	v_pk_fma_f32 v[38:39], v[8:9], v[50:51], v[38:39] op_sel:[0,1,0] op_sel_hi:[1,1,1]
	v_pk_fma_f32 v[10:11], v[44:45], v[52:53], v[10:11] op_sel_hi:[1,0,1]
	v_pk_fma_f32 v[38:39], v[10:11], v[52:53], v[38:39] op_sel:[0,1,0] op_sel_hi:[1,1,1]
	v_pk_fma_f32 v[12:13], v[44:45], v[54:55], v[12:13] op_sel_hi:[1,0,1]
	v_pk_fma_f32 v[38:39], v[12:13], v[54:55], v[38:39] op_sel:[0,1,0] op_sel_hi:[1,1,1]
	v_pk_fma_f32 v[14:15], v[44:45], v[56:57], v[14:15] op_sel_hi:[1,0,1]
	v_pk_fma_f32 v[38:39], v[14:15], v[56:57], v[38:39] op_sel:[0,1,0] op_sel_hi:[1,1,1]
	v_pk_fma_f32 v[16:17], v[44:45], v[58:59], v[16:17] op_sel_hi:[1,0,1]
	v_pk_fma_f32 v[38:39], v[16:17], v[58:59], v[38:39] op_sel:[0,1,0] op_sel_hi:[1,1,1]
	v_pk_fma_f32 v[18:19], v[44:45], v[60:61], v[18:19] op_sel_hi:[1,0,1]
	v_pk_fma_f32 v[38:39], v[18:19], v[60:61], v[38:39] op_sel:[0,1,0] op_sel_hi:[1,1,1]
	v_pk_fma_f32 v[20:21], v[44:45], v[62:63], v[20:21] op_sel_hi:[1,0,1]
	v_pk_fma_f32 v[38:39], v[20:21], v[62:63], v[38:39] op_sel:[0,1,0] op_sel_hi:[1,1,1]
	s_add_u32 s14, s14, 0x1000
	s_addc_u32 s15, s15, 0
	v_add_f32_dpp v38, v38, v38 quad_perm:[1,0,3,2] row_mask:0xf bank_mask:0xf bound_ctrl:1
	v_add_f32_dpp v39, v39, v39 quad_perm:[1,0,3,2] row_mask:0xf bank_mask:0xf bound_ctrl:1
	s_nop 0
	v_add_f32_dpp v38, v38, v38 quad_perm:[2,3,0,1] row_mask:0xf bank_mask:0xf bound_ctrl:1
	v_add_f32_dpp v39, v39, v39 quad_perm:[2,3,0,1] row_mask:0xf bank_mask:0xf bound_ctrl:1
	s_nop 0
	v_add_f32_dpp v38, v38, v38 row_half_mirror row_mask:0xf bank_mask:0xf bound_ctrl:1
	v_add_f32_dpp v39, v39, v39 row_half_mirror row_mask:0xf bank_mask:0xf bound_ctrl:1
	s_nop 0
	v_add_f32_dpp v38, v38, v38 row_mirror row_mask:0xf bank_mask:0xf bound_ctrl:1
	v_add_f32_dpp v39, v39, v39 row_mirror row_mask:0xf bank_mask:0xf bound_ctrl:1
	v_pk_mul_f32 v[38:39], v[38:39], v[40:41] op_sel:[0,1] op_sel_hi:[1,1]
	v_cvt_pk_bf16_f32 v47, v38, v39
	s_mov_b64 exec, s[2:3]
	global_store_dword v46, v47, s[14:15] offset:-4096
	s_mov_b64 exec, -1
	ds_read_b128 v[48:51], v24 offset:8192
	ds_read_b128 v[52:55], v24 offset:8448
	ds_read_b128 v[56:59], v24 offset:8704
	ds_read_b128 v[60:63], v24 offset:8960
	ds_read_b64 v[64:65], v25 offset:20480
	s_waitcnt lgkmcnt(5)
	v_pk_mul_f32 v[40:41], v[40:41], v[42:43]
	v_pk_mul_f32 v[44:45], v[82:83], v[40:41] op_sel_hi:[1,0]
	v_pk_fma_f32 v[6:7], v[44:45], v[66:67], v[6:7] op_sel_hi:[1,0,1]
	v_pk_mul_f32 v[38:39], v[6:7], v[66:67] op_sel:[0,1] op_sel_hi:[1,1]
	v_pk_fma_f32 v[8:9], v[44:45], v[68:69], v[8:9] op_sel_hi:[1,0,1]
	v_pk_fma_f32 v[38:39], v[8:9], v[68:69], v[38:39] op_sel:[0,1,0] op_sel_hi:[1,1,1]
	v_pk_fma_f32 v[10:11], v[44:45], v[70:71], v[10:11] op_sel_hi:[1,0,1]
	v_pk_fma_f32 v[38:39], v[10:11], v[70:71], v[38:39] op_sel:[0,1,0] op_sel_hi:[1,1,1]
	v_pk_fma_f32 v[12:13], v[44:45], v[72:73], v[12:13] op_sel_hi:[1,0,1]
	v_pk_fma_f32 v[38:39], v[12:13], v[72:73], v[38:39] op_sel:[0,1,0] op_sel_hi:[1,1,1]
	v_pk_fma_f32 v[14:15], v[44:45], v[74:75], v[14:15] op_sel_hi:[1,0,1]
	v_pk_fma_f32 v[38:39], v[14:15], v[74:75], v[38:39] op_sel:[0,1,0] op_sel_hi:[1,1,1]
	v_pk_fma_f32 v[16:17], v[44:45], v[76:77], v[16:17] op_sel_hi:[1,0,1]
	v_pk_fma_f32 v[38:39], v[16:17], v[76:77], v[38:39] op_sel:[0,1,0] op_sel_hi:[1,1,1]
	v_pk_fma_f32 v[18:19], v[44:45], v[78:79], v[18:19] op_sel_hi:[1,0,1]
	v_pk_fma_f32 v[38:39], v[18:19], v[78:79], v[38:39] op_sel:[0,1,0] op_sel_hi:[1,1,1]
	v_pk_fma_f32 v[20:21], v[44:45], v[80:81], v[20:21] op_sel_hi:[1,0,1]
	v_pk_fma_f32 v[38:39], v[20:21], v[80:81], v[38:39] op_sel:[0,1,0] op_sel_hi:[1,1,1]
	s_add_u32 s14, s14, 0x1000
	s_addc_u32 s15, s15, 0
	v_add_f32_dpp v38, v38, v38 quad_perm:[1,0,3,2] row_mask:0xf bank_mask:0xf bound_ctrl:1
	v_add_f32_dpp v39, v39, v39 quad_perm:[1,0,3,2] row_mask:0xf bank_mask:0xf bound_ctrl:1
	s_nop 0
	v_add_f32_dpp v38, v38, v38 quad_perm:[2,3,0,1] row_mask:0xf bank_mask:0xf bound_ctrl:1
	v_add_f32_dpp v39, v39, v39 quad_perm:[2,3,0,1] row_mask:0xf bank_mask:0xf bound_ctrl:1
	s_nop 0
	v_add_f32_dpp v38, v38, v38 row_half_mirror row_mask:0xf bank_mask:0xf bound_ctrl:1
	v_add_f32_dpp v39, v39, v39 row_half_mirror row_mask:0xf bank_mask:0xf bound_ctrl:1
	s_nop 0
	v_add_f32_dpp v38, v38, v38 row_mirror row_mask:0xf bank_mask:0xf bound_ctrl:1
	v_add_f32_dpp v39, v39, v39 row_mirror row_mask:0xf bank_mask:0xf bound_ctrl:1
	v_pk_mul_f32 v[38:39], v[38:39], v[40:41] op_sel:[0,1] op_sel_hi:[1,1]
	v_cvt_pk_bf16_f32 v47, v38, v39
	s_mov_b64 exec, s[2:3]
	global_store_dword v46, v47, s[14:15] offset:-4096
	s_mov_b64 exec, -1
	s_waitcnt vmcnt(8)
	v_lshlrev_b32_e32 v108, 16, v84
	v_lshlrev_b32_e32 v109, 16, v85
	v_and_b32_e32 v110, s17, v84
	v_and_b32_e32 v111, s17, v85
	v_lshlrev_b32_e32 v112, 16, v86
	v_lshlrev_b32_e32 v113, 16, v87
	v_and_b32_e32 v114, s17, v86
	v_and_b32_e32 v115, s17, v87
	v_lshlrev_b32_e32 v116, 16, v88
	v_and_b32_e32 v117, s17, v88
	ds_write_b128 v26, v[108:111] offset:0
	ds_write_b128 v26, v[112:115] offset:8192
	ds_write_b64 v27, v[90:91]
	ds_write_b64 v28, v[116:117]
	s_mov_b32 s0, s20
	s_mov_b32 s20, s21
	s_mov_b32 s21, s22
	s_mov_b32 s22, s0
	v_mov_b32_e32 v22, v24
	v_mov_b32_e32 v23, v25
	v_add_u32_e32 v24, s21, v2
	v_add_u32_e32 v25, s21, v3
	v_add_u32_e32 v26, s22, v29
	v_add_u32_e32 v27, s22, v30
	v_add_u32_e32 v28, s22, v31
	s_waitcnt lgkmcnt(0)
	s_barrier
	s_add_i32 s16, s16, 8
	s_cmpk_lt_u32 s16, 0x800
	s_cbranch_scc1 .Lret2_loop
	v_readlane_b32 s0, v255, 18
	v_readlane_b32 s1, v255, 19
	s_load_dwordx2 s[2:3], s[0:1], 0xe8
	s_lshr_b32 s0, s23, 5
	s_lshl_b32 s4, s0, 17
	s_add_u32 s4, s4, 78430464
	v_lshl_add_u32 v42, v46, 1, v4
	s_waitcnt lgkmcnt(0)
	s_add_u32 s2, s2, s4
	s_addc_u32 s3, s3, 0
	v_pk_mul_f32 v[6:7], v[6:7], v[40:41] op_sel:[0,1] op_sel_hi:[1,1]
	v_pk_mul_f32 v[8:9], v[8:9], v[40:41] op_sel:[0,1] op_sel_hi:[1,1]
	v_pk_mul_f32 v[10:11], v[10:11], v[40:41] op_sel:[0,1] op_sel_hi:[1,1]
	v_pk_mul_f32 v[12:13], v[12:13], v[40:41] op_sel:[0,1] op_sel_hi:[1,1]
	v_pk_mul_f32 v[14:15], v[14:15], v[40:41] op_sel:[0,1] op_sel_hi:[1,1]
	v_pk_mul_f32 v[16:17], v[16:17], v[40:41] op_sel:[0,1] op_sel_hi:[1,1]
	v_pk_mul_f32 v[18:19], v[18:19], v[40:41] op_sel:[0,1] op_sel_hi:[1,1]
	v_pk_mul_f32 v[20:21], v[20:21], v[40:41] op_sel:[0,1] op_sel_hi:[1,1]
	global_store_dwordx2 v42, v[6:7], s[2:3] offset:0
	global_store_dwordx2 v42, v[8:9], s[2:3] offset:1024
	global_store_dwordx2 v42, v[10:11], s[2:3] offset:2048
	global_store_dwordx2 v42, v[12:13], s[2:3] offset:3072
	s_add_u32 s2, s2, 0x1000
	s_addc_u32 s3, s3, 0
	global_store_dwordx2 v42, v[14:15], s[2:3] offset:0
	global_store_dwordx2 v42, v[16:17], s[2:3] offset:1024
	global_store_dwordx2 v42, v[18:19], s[2:3] offset:2048
	global_store_dwordx2 v42, v[20:21], s[2:3] offset:3072
	s_add_i32 s23, s23, s19
	s_waitcnt vmcnt(0)
	s_cmpk_lt_i32 s23, 0x400
	s_cbranch_scc1 .Lret2_item
	s_branch .LBB0_57

.LBB0_123:
	s_andn2_b64 vcc, exec, s[0:1]
	s_cbranch_vccnz .LBB0_252
	s_lshl_b32 s0, s58, 2
	s_bfe_u32 s1, s26, 0x20006
	s_or_b32 s27, s1, s0
	s_lshl_b32 s28, s59, 2
	s_cmpk_lt_i32 s27, 0x400
	s_cselect_b64 s[2:3], -1, 0
	v_readlane_b32 s0, v255, 15
	v_cndmask_b32_e64 v0, 0, 1, s[2:3]
	s_cmp_lt_i32 s0, 4
	s_mov_b64 s[0:1], -1
	v_cmp_ne_u32_e64 s[6:7], 1, v0
	s_cbranch_scc1 .LBB0_186
	s_and_b64 vcc, exec, s[6:7]
	s_cbranch_vccnz .LBB0_185
	v_readlane_b32 s0, v255, 18
	v_readlane_b32 s1, v255, 19
	s_load_dwordx2 s[34:35], s[0:1], 0xe8
	s_load_dwordx2 s[2:3], s[0:1], 0xf0
	v_readlane_b32 s5, v255, 15
	v_and_b32_e32 v104, 15, v198
	v_lshrrev_b32_e32 v5, 4, v198
	v_lshlrev_b32_e32 v2, 4, v104
	s_mov_b32 s17, 0xffff0000
	s_mov_b32 s29, 0x3fb8aa3b
	v_mov_b32_e32 v29, 0xc0400000
	s_mov_b32 s30, s27
	s_mov_b32 s36, s5
	v_and_b32_e32 v104, 3, v198
	v_lshrrev_b32_e32 v105, 2, v198
	v_lshlrev_b32_e32 v69, 8, v104
	v_lshl_add_u32 v69, v105, 4, v69
	s_lshl_b32 s0, s5, 10
	s_add_u32 s0, s0, 0
	v_add_u32_e32 v69, s0, v69
	s_lshl_b32 s0, s5, 9
	s_add_u32 s0, s0, 8192
	v_lshl_add_u32 v70, v198, 3, s0
	v_min_u32_e32 v104, 15, v198
	s_lshl_b32 s0, s5, 8
	s_add_u32 s0, s0, 12288
	v_lshl_add_u32 v71, v104, 3, s0
	v_min_u32_e32 v105, 2, v198
	v_lshlrev_b32_e32 v78, 2, v105
	s_lshl_b32 s0, s5, 4
	s_add_u32 s0, s0, 14336
	v_add_u32_e32 v72, s0, v78
	v_lshlrev_b32_e32 v74, 2, v198
	v_and_b32_e32 v105, 31, v198
	v_lshlrev_b32_e32 v75, 2, v105
	v_cmp_gt_u32_e32 vcc, 32, v198
	v_add_u32_e32 v105, 1024, v75
	s_nop 1
	v_cndmask_b32_e32 v75, v75, v105, vcc
	v_and_b32_e32 v105, 15, v198
	v_lshlrev_b32_e32 v73, 4, v105
	v_add_u32_e32 v73, 14592, v73
	v_and_b32_e32 v105, 7, v198
	v_lshlrev_b32_e32 v79, 7, v105
	s_waitcnt lgkmcnt(0)
	s_mov_b64 s[0:1], s[2:3]
.Lml2_item:
	v_readlane_b32 s2, v255, 18
	v_readlane_b32 s3, v255, 19
	s_load_dwordx2 s[0:1], s[2:3], 0xf0
	s_lshr_b32 s2, s30, 4
	s_and_b32 s3, s30, 15
	s_mov_b32 s31, s3
	s_mov_b32 s21, s3
	s_lshl_b32 s4, s3, 4
	v_lshl_add_u32 v4, v5, 2, s4
	s_and_b32 s4, s3, 3
	s_lshl_b32 s4, s4, 5
	s_add_u32 s4, s4, 128
	v_lshl_add_u32 v3, v5, 3, s4
	s_and_b32 s4, s3, 12
	s_lshl_b32 s4, s4, 4
	v_min_u32_e32 v104, 15, v198
	v_lshl_add_u32 v76, v104, 2, s4
	s_and_b32 s5, s2, 7
	s_lshl_b32 s3, s5, 7
	s_add_u32 s4, s4, s3
	s_add_u32 s4, s4, 2048
	v_lshl_add_u32 v77, v104, 2, s4
	s_lshr_b32 s4, s2, 3
	s_waitcnt lgkmcnt(0)
	v_readlane_b32 s3, v255, 15
	s_mul_i32 s8, s4, 0xc00000
	s_mul_i32 s9, s3, 0x1800
	s_add_u32 s8, s8, s9
	s_lshl_b32 s9, s5, 8
	s_add_u32 s8, s8, s9
	s_add_u32 s8, s8, 0xb38d900
	s_add_u32 s8, s34, s8
	s_addc_u32 s9, s35, 0
	s_lshl_b32 s10, s4, 25
	s_lshl_b32 s11, s3, 14
	s_add_u32 s10, s10, s11
	s_lshl_b32 s11, s5, 7
	s_add_u32 s10, s10, s11
	s_add_u32 s10, s10, 62659584
	s_add_u32 s10, s0, s10
	s_addc_u32 s11, s1, 0
	s_lshl_b32 s12, s4, 18
	s_lshl_b32 s13, s3, 7
	s_add_u32 s12, s12, s13
	s_lshl_b32 s13, s5, 4
	s_add_u32 s12, s12, s13
	s_add_u32 s12, s12, 0x37b8400
	s_add_u32 s12, s0, s12
	s_addc_u32 s13, s1, 0
	s_lshl_b32 s14, s4, 23
	s_lshl_b32 s15, s5, 8
	s_add_u32 s14, s14, s15
	s_add_u32 s14, s14, 333188096
	s_add_u32 s14, s0, s14
	s_addc_u32 s15, s1, 0
	s_lshl_b32 s22, s4, 18
	s_lshl_b32 s23, s5, 4
	s_add_u32 s22, s22, s23
	s_add_u32 s22, s22, 0x39bc400
	s_add_u32 s22, s0, s22
	s_addc_u32 s23, s1, 0
	s_mov_b64 s[24:25], s[22:23]
	v_mov_b32_e32 v0, 0
	s_movk_i32 s18, 256
	s_movk_i32 s19, 16640
	s_mov_b32 s20, 33024
	v_add_u32_e32 v64, s18, v69
	v_add_u32_e32 v65, s18, v70
	v_add_u32_e32 v66, s18, v71
	v_add_u32_e32 v67, s18, v72
	v_add_u32_e32 v68, s18, v73
	global_load_dword v80, v74, s[8:9]
	global_load_dword v81, v74, s[8:9] offset:-2048
	global_load_dword v83, v76, s[8:9] offset:2048
	global_load_dword v82, v75, s[10:11]
	global_load_dword v84, v77, s[10:11]
	global_load_dword v85, v78, s[12:13]
	s_cmp_lg_u32 s36, 4
	s_cbranch_scc1 .Lml2_nsl0
	global_load_dwordx2 v[86:87], v79, s[22:23]
.Lml2_nsl0:
	s_add_u32 s22, s22, 0x400
	s_addc_u32 s23, s23, 0
	s_add_u32 s8, s8, 0xc000
	s_addc_u32 s9, s9, 0
	s_add_u32 s10, s10, 0x20000
	s_addc_u32 s11, s11, 0
	s_add_u32 s12, s12, 0x400
	s_addc_u32 s13, s13, 0
	s_waitcnt vmcnt(0)
	v_lshlrev_b32_e32 v88, 16, v80
	v_lshlrev_b32_e32 v89, 16, v81
	v_and_b32_e32 v90, s17, v80
	v_and_b32_e32 v91, s17, v81
	v_lshlrev_b32_e32 v92, 16, v82
	v_and_b32_e32 v93, s17, v82
	v_lshlrev_b32_e32 v94, 16, v83
	v_and_b32_e32 v95, s17, v83
	v_lshlrev_b32_e32 v96, 16, v84
	v_and_b32_e32 v97, s17, v84
	ds_write_b128 v64, v[88:91]
	ds_write_b64 v65, v[92:93]
	ds_write_b64 v66, v[94:95]
	ds_write_b64 v66, v[96:97] offset:128
	ds_write_b32 v67, v85
	s_cmp_lg_u32 s36, 4
	s_cbranch_scc1 .Lml2_nsc0
	v_mov_b32_e32 v98, v87
	s_nop 1
	v_add_f32_dpp v98, v98, v98 row_shr:1 row_mask:0xf bank_mask:0xf bound_ctrl:1
	s_nop 1
	v_add_f32_dpp v98, v98, v98 row_shr:2 row_mask:0xf bank_mask:0xf bound_ctrl:1
	s_nop 1
	v_add_f32_dpp v98, v98, v98 row_shr:4 row_mask:0xf bank_mask:0xf bound_ctrl:1
	s_nop 1
	v_sub_f32_e32 v99, v86, v98
	s_nop 1
	v_max_f32_dpp v99, v99, v99 row_shr:1 row_mask:0xf bank_mask:0xf
	s_nop 1
	v_max_f32_dpp v99, v99, v99 row_shr:2 row_mask:0xf bank_mask:0xf
	s_nop 1
	v_max_f32_dpp v99, v99, v99 row_shr:4 row_mask:0xf bank_mask:0xf
	s_nop 1
	v_max_f32_e32 v99, v99, v0
	v_add_f32_e32 v103, v98, v99
	v_mov_b32_e32 v105, v0
	s_nop 0
	v_mov_b32_dpp v105, v103 row_shr:1 row_mask:0xf bank_mask:0xf
	v_sub_f32_e32 v104, v86, v103
	v_add_f32_e32 v105, v87, v105
	v_fma_f32 v104, v104, s29, v29
	v_sub_f32_e32 v105, v105, v103
	v_exp_f32_e32 v101, v104
	v_mul_f32_e32 v105, s29, v105
	v_mul_f32_e32 v104, 0xbfb8aa3b, v103
	v_exp_f32_e32 v100, v105
	v_exp_f32_e32 v102, v104
	v_readlane_b32 s4, v103, 7
	s_nop 3
	v_mov_b32_e32 v0, s4
	ds_write_b128 v68, v[100:103]
.Lml2_nsc0:
	v_add_u32_e32 v64, s19, v69
	v_add_u32_e32 v65, s19, v70
	v_add_u32_e32 v66, s19, v71
	v_add_u32_e32 v67, s19, v72
	v_add_u32_e32 v68, s19, v73
	global_load_dword v80, v74, s[8:9]
	global_load_dword v81, v74, s[8:9] offset:-2048
	global_load_dword v83, v76, s[8:9] offset:2048
	global_load_dword v82, v75, s[10:11]
	global_load_dword v84, v77, s[10:11]
	global_load_dword v85, v78, s[12:13]
	s_cmp_lg_u32 s36, 4
	s_cbranch_scc1 .Lml2_nsl1
	global_load_dwordx2 v[86:87], v79, s[22:23]

.Lml2_nsc1:
	v_add_u32_e32 v64, s20, v69
	v_add_u32_e32 v65, s20, v70
	v_add_u32_e32 v66, s20, v71
	v_add_u32_e32 v67, s20, v72
	v_add_u32_e32 v68, s20, v73
	v_add_u32_e32 v58, s18, v2
	v_add_u32_e32 v59, s18, v3
	v_mov_b32_e32 v60, s18
	v_add_u32_e32 v61, s19, v2
	v_add_u32_e32 v62, s19, v3
	v_mov_b32_e32 v63, s19
	v_mov_b32_e32 v6, 0
	v_mov_b32_e32 v7, 0
	v_mov_b32_e32 v8, 0
	v_mov_b32_e32 v9, 0
	v_mov_b32_e32 v10, 0
	v_mov_b32_e32 v11, 0
	v_mov_b32_e32 v12, 0
	v_mov_b32_e32 v13, 0
	v_mov_b32_e32 v14, 0
	v_mov_b32_e32 v15, 0
	v_mov_b32_e32 v16, 0
	v_mov_b32_e32 v17, 0
	s_mov_b32 s16, 0
	s_waitcnt vmcnt(0) lgkmcnt(0)
	s_barrier
	ds_read_b128 v[30:33], v58 offset:8192
	ds_read_b128 v[34:37], v58 offset:8448
	ds_read_b64 v[38:39], v59 offset:12288
	ds_read_b128 v[40:43], v60 offset:14592
.Lml2_loop:
	global_load_dword v80, v74, s[8:9]
	global_load_dword v81, v74, s[8:9] offset:-2048
	global_load_dword v83, v76, s[8:9] offset:2048
	global_load_dword v82, v75, s[10:11]
	global_load_dword v84, v77, s[10:11]
	global_load_dword v85, v78, s[12:13]
	s_cmp_lg_u32 s36, 4
	s_cbranch_scc1 .Lml2_nsl2
	global_load_dwordx2 v[86:87], v79, s[22:23]
.Lml2_nsl2:
	s_add_u32 s22, s22, 0x400
	s_addc_u32 s23, s23, 0
	s_add_u32 s8, s8, 0xc000
	s_addc_u32 s9, s9, 0
	s_add_u32 s10, s10, 0x20000
	s_addc_u32 s11, s11, 0
	s_add_u32 s12, s12, 0x400
	s_addc_u32 s13, s13, 0
	ds_read_b128 v[44:47], v58 offset:8704
	ds_read_b128 v[48:51], v58 offset:8960
	ds_read_b64 v[52:53], v59 offset:12544
	ds_read_b128 v[54:57], v60 offset:14608
	s_waitcnt lgkmcnt(4)
	v_pk_mul_f32 v[18:19], v[30:31], v[40:41] op_sel:[0,1] op_sel_hi:[1,1]
	v_pk_mul_f32 v[20:21], v[32:33], v[40:41] op_sel:[0,1] op_sel_hi:[1,1]
	v_pk_mul_f32 v[22:23], v[38:39], v[18:19] op_sel:[0,0] op_sel_hi:[1,0]
	v_pk_fma_f32 v[6:7], v[6:7], v[40:41], v[22:23] op_sel_hi:[1,0,1]
	v_pk_mul_f32 v[26:27], v[6:7], v[34:35] op_sel_hi:[1,0]
	v_pk_mul_f32 v[24:25], v[38:39], v[18:19] op_sel:[0,1] op_sel_hi:[1,1]
	v_pk_fma_f32 v[8:9], v[8:9], v[40:41], v[24:25] op_sel_hi:[1,0,1]
	v_pk_fma_f32 v[26:27], v[8:9], v[34:35], v[26:27] op_sel:[0,1,0] op_sel_hi:[1,1,1]
	v_pk_mul_f32 v[22:23], v[38:39], v[20:21] op_sel:[0,0] op_sel_hi:[1,0]
	v_pk_fma_f32 v[10:11], v[10:11], v[40:41], v[22:23] op_sel_hi:[1,0,1]
	v_pk_fma_f32 v[26:27], v[10:11], v[36:37], v[26:27] op_sel:[0,0,0] op_sel_hi:[1,0,1]
	v_pk_mul_f32 v[24:25], v[38:39], v[20:21] op_sel:[0,1] op_sel_hi:[1,1]
	v_pk_fma_f32 v[12:13], v[12:13], v[40:41], v[24:25] op_sel_hi:[1,0,1]
	v_pk_fma_f32 v[26:27], v[12:13], v[36:37], v[26:27] op_sel:[0,1,0] op_sel_hi:[1,1,1]
	v_pk_fma_f32 v[14:15], v[14:15], v[40:41], v[18:19] op_sel_hi:[1,0,1]
	v_pk_fma_f32 v[16:17], v[16:17], v[40:41], v[20:21] op_sel_hi:[1,0,1]
	v_add_f32_dpp v26, v26, v26 quad_perm:[1,0,3,2] row_mask:0xf bank_mask:0xf bound_ctrl:1
	v_add_f32_dpp v27, v27, v27 quad_perm:[1,0,3,2] row_mask:0xf bank_mask:0xf bound_ctrl:1
	s_add_u32 s14, s14, 0x1000
	v_add_f32_dpp v26, v26, v26 quad_perm:[2,3,0,1] row_mask:0xf bank_mask:0xf bound_ctrl:1
	v_add_f32_dpp v27, v27, v27 quad_perm:[2,3,0,1] row_mask:0xf bank_mask:0xf bound_ctrl:1
	s_addc_u32 s15, s15, 0
	v_add_f32_dpp v26, v26, v26 row_half_mirror row_mask:0xf bank_mask:0xf bound_ctrl:1
	v_add_f32_dpp v27, v27, v27 row_half_mirror row_mask:0xf bank_mask:0xf bound_ctrl:1
	s_cmp_eq_u32 s21, 0
	v_add_f32_dpp v26, v26, v26 row_mirror row_mask:0xf bank_mask:0xf bound_ctrl:1
	v_add_f32_dpp v27, v27, v27 row_mirror row_mask:0xf bank_mask:0xf bound_ctrl:1
	s_cbranch_scc1 .Lml2_den0
.Lml2_back0:
	v_cvt_pk_bf16_f32 v28, v26, v27
	global_store_dword v4, v28, s[14:15] offset:-4096
	ds_read_b128 v[30:33], v58 offset:9216
	ds_read_b128 v[34:37], v58 offset:9472
	ds_read_b64 v[38:39], v59 offset:12800
	ds_read_b128 v[40:43], v60 offset:14624
	s_waitcnt lgkmcnt(4)
	v_pk_mul_f32 v[18:19], v[44:45], v[54:55] op_sel:[0,1] op_sel_hi:[1,1]
	v_pk_mul_f32 v[20:21], v[46:47], v[54:55] op_sel:[0,1] op_sel_hi:[1,1]
	v_pk_mul_f32 v[22:23], v[52:53], v[18:19] op_sel:[0,0] op_sel_hi:[1,0]
	v_pk_fma_f32 v[6:7], v[6:7], v[54:55], v[22:23] op_sel_hi:[1,0,1]
	v_pk_mul_f32 v[26:27], v[6:7], v[48:49] op_sel_hi:[1,0]
	v_pk_mul_f32 v[24:25], v[52:53], v[18:19] op_sel:[0,1] op_sel_hi:[1,1]
	v_pk_fma_f32 v[8:9], v[8:9], v[54:55], v[24:25] op_sel_hi:[1,0,1]
	v_pk_fma_f32 v[26:27], v[8:9], v[48:49], v[26:27] op_sel:[0,1,0] op_sel_hi:[1,1,1]
	v_pk_mul_f32 v[22:23], v[52:53], v[20:21] op_sel:[0,0] op_sel_hi:[1,0]
	v_pk_fma_f32 v[10:11], v[10:11], v[54:55], v[22:23] op_sel_hi:[1,0,1]
	v_pk_fma_f32 v[26:27], v[10:11], v[50:51], v[26:27] op_sel:[0,0,0] op_sel_hi:[1,0,1]
	v_pk_mul_f32 v[24:25], v[52:53], v[20:21] op_sel:[0,1] op_sel_hi:[1,1]
	v_pk_fma_f32 v[12:13], v[12:13], v[54:55], v[24:25] op_sel_hi:[1,0,1]
	v_pk_fma_f32 v[26:27], v[12:13], v[50:51], v[26:27] op_sel:[0,1,0] op_sel_hi:[1,1,1]
	v_pk_fma_f32 v[14:15], v[14:15], v[54:55], v[18:19] op_sel_hi:[1,0,1]
	v_pk_fma_f32 v[16:17], v[16:17], v[54:55], v[20:21] op_sel_hi:[1,0,1]
	v_add_f32_dpp v26, v26, v26 quad_perm:[1,0,3,2] row_mask:0xf bank_mask:0xf bound_ctrl:1
	v_add_f32_dpp v27, v27, v27 quad_perm:[1,0,3,2] row_mask:0xf bank_mask:0xf bound_ctrl:1
	s_add_u32 s14, s14, 0x1000
	v_add_f32_dpp v26, v26, v26 quad_perm:[2,3,0,1] row_mask:0xf bank_mask:0xf bound_ctrl:1
	v_add_f32_dpp v27, v27, v27 quad_perm:[2,3,0,1] row_mask:0xf bank_mask:0xf bound_ctrl:1
	s_addc_u32 s15, s15, 0
	v_add_f32_dpp v26, v26, v26 row_half_mirror row_mask:0xf bank_mask:0xf bound_ctrl:1
	v_add_f32_dpp v27, v27, v27 row_half_mirror row_mask:0xf bank_mask:0xf bound_ctrl:1
	s_cmp_eq_u32 s21, 1
	v_add_f32_dpp v26, v26, v26 row_mirror row_mask:0xf bank_mask:0xf bound_ctrl:1
	v_add_f32_dpp v27, v27, v27 row_mirror row_mask:0xf bank_mask:0xf bound_ctrl:1
	s_cbranch_scc1 .Lml2_den1
.Lml2_back1:
	v_cvt_pk_bf16_f32 v28, v26, v27
	global_store_dword v4, v28, s[14:15] offset:-4096
	ds_read_b128 v[44:47], v58 offset:9728
	ds_read_b128 v[48:51], v58 offset:9984
	ds_read_b64 v[52:53], v59 offset:13056
	ds_read_b128 v[54:57], v60 offset:14640
	s_waitcnt lgkmcnt(4)
	v_pk_mul_f32 v[18:19], v[30:31], v[40:41] op_sel:[0,1] op_sel_hi:[1,1]
	v_pk_mul_f32 v[20:21], v[32:33], v[40:41] op_sel:[0,1] op_sel_hi:[1,1]
	v_pk_mul_f32 v[22:23], v[38:39], v[18:19] op_sel:[0,0] op_sel_hi:[1,0]
	v_pk_fma_f32 v[6:7], v[6:7], v[40:41], v[22:23] op_sel_hi:[1,0,1]
	v_pk_mul_f32 v[26:27], v[6:7], v[34:35] op_sel_hi:[1,0]
	v_pk_mul_f32 v[24:25], v[38:39], v[18:19] op_sel:[0,1] op_sel_hi:[1,1]
	v_pk_fma_f32 v[8:9], v[8:9], v[40:41], v[24:25] op_sel_hi:[1,0,1]
	v_pk_fma_f32 v[26:27], v[8:9], v[34:35], v[26:27] op_sel:[0,1,0] op_sel_hi:[1,1,1]
	v_pk_mul_f32 v[22:23], v[38:39], v[20:21] op_sel:[0,0] op_sel_hi:[1,0]
	v_pk_fma_f32 v[10:11], v[10:11], v[40:41], v[22:23] op_sel_hi:[1,0,1]
	v_pk_fma_f32 v[26:27], v[10:11], v[36:37], v[26:27] op_sel:[0,0,0] op_sel_hi:[1,0,1]
	v_pk_mul_f32 v[24:25], v[38:39], v[20:21] op_sel:[0,1] op_sel_hi:[1,1]
	v_pk_fma_f32 v[12:13], v[12:13], v[40:41], v[24:25] op_sel_hi:[1,0,1]
	v_pk_fma_f32 v[26:27], v[12:13], v[36:37], v[26:27] op_sel:[0,1,0] op_sel_hi:[1,1,1]
	v_pk_fma_f32 v[14:15], v[14:15], v[40:41], v[18:19] op_sel_hi:[1,0,1]
	v_pk_fma_f32 v[16:17], v[16:17], v[40:41], v[20:21] op_sel_hi:[1,0,1]
	v_add_f32_dpp v26, v26, v26 quad_perm:[1,0,3,2] row_mask:0xf bank_mask:0xf bound_ctrl:1
	v_add_f32_dpp v27, v27, v27 quad_perm:[1,0,3,2] row_mask:0xf bank_mask:0xf bound_ctrl:1
	s_add_u32 s14, s14, 0x1000
	v_add_f32_dpp v26, v26, v26 quad_perm:[2,3,0,1] row_mask:0xf bank_mask:0xf bound_ctrl:1
	v_add_f32_dpp v27, v27, v27 quad_perm:[2,3,0,1] row_mask:0xf bank_mask:0xf bound_ctrl:1
	s_addc_u32 s15, s15, 0
	v_add_f32_dpp v26, v26, v26 row_half_mirror row_mask:0xf bank_mask:0xf bound_ctrl:1
	v_add_f32_dpp v27, v27, v27 row_half_mirror row_mask:0xf bank_mask:0xf bound_ctrl:1
	s_cmp_eq_u32 s21, 2
	v_add_f32_dpp v26, v26, v26 row_mirror row_mask:0xf bank_mask:0xf bound_ctrl:1
	v_add_f32_dpp v27, v27, v27 row_mirror row_mask:0xf bank_mask:0xf bound_ctrl:1
	s_cbranch_scc1 .Lml2_den2
.Lml2_back2:
	v_cvt_pk_bf16_f32 v28, v26, v27
	global_store_dword v4, v28, s[14:15] offset:-4096
	ds_read_b128 v[30:33], v58 offset:10240
	ds_read_b128 v[34:37], v58 offset:10496
	ds_read_b64 v[38:39], v59 offset:13312
	ds_read_b128 v[40:43], v60 offset:14656
	s_waitcnt lgkmcnt(4)
	v_pk_mul_f32 v[18:19], v[44:45], v[54:55] op_sel:[0,1] op_sel_hi:[1,1]
	v_pk_mul_f32 v[20:21], v[46:47], v[54:55] op_sel:[0,1] op_sel_hi:[1,1]
	v_pk_mul_f32 v[22:23], v[52:53], v[18:19] op_sel:[0,0] op_sel_hi:[1,0]
	v_pk_fma_f32 v[6:7], v[6:7], v[54:55], v[22:23] op_sel_hi:[1,0,1]
	v_pk_mul_f32 v[26:27], v[6:7], v[48:49] op_sel_hi:[1,0]
	v_pk_mul_f32 v[24:25], v[52:53], v[18:19] op_sel:[0,1] op_sel_hi:[1,1]
	v_pk_fma_f32 v[8:9], v[8:9], v[54:55], v[24:25] op_sel_hi:[1,0,1]
	v_pk_fma_f32 v[26:27], v[8:9], v[48:49], v[26:27] op_sel:[0,1,0] op_sel_hi:[1,1,1]
	v_pk_mul_f32 v[22:23], v[52:53], v[20:21] op_sel:[0,0] op_sel_hi:[1,0]
	v_pk_fma_f32 v[10:11], v[10:11], v[54:55], v[22:23] op_sel_hi:[1,0,1]
	v_pk_fma_f32 v[26:27], v[10:11], v[50:51], v[26:27] op_sel:[0,0,0] op_sel_hi:[1,0,1]
	v_pk_mul_f32 v[24:25], v[52:53], v[20:21] op_sel:[0,1] op_sel_hi:[1,1]
	v_pk_fma_f32 v[12:13], v[12:13], v[54:55], v[24:25] op_sel_hi:[1,0,1]
	v_pk_fma_f32 v[26:27], v[12:13], v[50:51], v[26:27] op_sel:[0,1,0] op_sel_hi:[1,1,1]
	v_pk_fma_f32 v[14:15], v[14:15], v[54:55], v[18:19] op_sel_hi:[1,0,1]
	v_pk_fma_f32 v[16:17], v[16:17], v[54:55], v[20:21] op_sel_hi:[1,0,1]
	v_add_f32_dpp v26, v26, v26 quad_perm:[1,0,3,2] row_mask:0xf bank_mask:0xf bound_ctrl:1
	v_add_f32_dpp v27, v27, v27 quad_perm:[1,0,3,2] row_mask:0xf bank_mask:0xf bound_ctrl:1
	s_add_u32 s14, s14, 0x1000
	v_add_f32_dpp v26, v26, v26 quad_perm:[2,3,0,1] row_mask:0xf bank_mask:0xf bound_ctrl:1
	v_add_f32_dpp v27, v27, v27 quad_perm:[2,3,0,1] row_mask:0xf bank_mask:0xf bound_ctrl:1
	s_addc_u32 s15, s15, 0
	v_add_f32_dpp v26, v26, v26 row_half_mirror row_mask:0xf bank_mask:0xf bound_ctrl:1
	v_add_f32_dpp v27, v27, v27 row_half_mirror row_mask:0xf bank_mask:0xf bound_ctrl:1
	s_cmp_eq_u32 s21, 3
	v_add_f32_dpp v26, v26, v26 row_mirror row_mask:0xf bank_mask:0xf bound_ctrl:1
	v_add_f32_dpp v27, v27, v27 row_mirror row_mask:0xf bank_mask:0xf bound_ctrl:1
	s_cbranch_scc1 .Lml2_den3
.Lml2_back3:
	v_cvt_pk_bf16_f32 v28, v26, v27
	global_store_dword v4, v28, s[14:15] offset:-4096
	ds_read_b128 v[44:47], v58 offset:10752
	ds_read_b128 v[48:51], v58 offset:11008
	ds_read_b64 v[52:53], v59 offset:13568
	ds_read_b128 v[54:57], v60 offset:14672
	s_waitcnt lgkmcnt(4)
	v_pk_mul_f32 v[18:19], v[30:31], v[40:41] op_sel:[0,1] op_sel_hi:[1,1]
	v_pk_mul_f32 v[20:21], v[32:33], v[40:41] op_sel:[0,1] op_sel_hi:[1,1]
	v_pk_mul_f32 v[22:23], v[38:39], v[18:19] op_sel:[0,0] op_sel_hi:[1,0]
	v_pk_fma_f32 v[6:7], v[6:7], v[40:41], v[22:23] op_sel_hi:[1,0,1]
	v_pk_mul_f32 v[26:27], v[6:7], v[34:35] op_sel_hi:[1,0]
	v_pk_mul_f32 v[24:25], v[38:39], v[18:19] op_sel:[0,1] op_sel_hi:[1,1]
	v_pk_fma_f32 v[8:9], v[8:9], v[40:41], v[24:25] op_sel_hi:[1,0,1]
	v_pk_fma_f32 v[26:27], v[8:9], v[34:35], v[26:27] op_sel:[0,1,0] op_sel_hi:[1,1,1]
	v_pk_mul_f32 v[22:23], v[38:39], v[20:21] op_sel:[0,0] op_sel_hi:[1,0]
	v_pk_fma_f32 v[10:11], v[10:11], v[40:41], v[22:23] op_sel_hi:[1,0,1]
	v_pk_fma_f32 v[26:27], v[10:11], v[36:37], v[26:27] op_sel:[0,0,0] op_sel_hi:[1,0,1]
	v_pk_mul_f32 v[24:25], v[38:39], v[20:21] op_sel:[0,1] op_sel_hi:[1,1]
	v_pk_fma_f32 v[12:13], v[12:13], v[40:41], v[24:25] op_sel_hi:[1,0,1]
	v_pk_fma_f32 v[26:27], v[12:13], v[36:37], v[26:27] op_sel:[0,1,0] op_sel_hi:[1,1,1]
	v_pk_fma_f32 v[14:15], v[14:15], v[40:41], v[18:19] op_sel_hi:[1,0,1]
	v_pk_fma_f32 v[16:17], v[16:17], v[40:41], v[20:21] op_sel_hi:[1,0,1]
	v_add_f32_dpp v26, v26, v26 quad_perm:[1,0,3,2] row_mask:0xf bank_mask:0xf bound_ctrl:1
	v_add_f32_dpp v27, v27, v27 quad_perm:[1,0,3,2] row_mask:0xf bank_mask:0xf bound_ctrl:1
	s_add_u32 s14, s14, 0x1000
	v_add_f32_dpp v26, v26, v26 quad_perm:[2,3,0,1] row_mask:0xf bank_mask:0xf bound_ctrl:1
	v_add_f32_dpp v27, v27, v27 quad_perm:[2,3,0,1] row_mask:0xf bank_mask:0xf bound_ctrl:1
	s_addc_u32 s15, s15, 0
	v_add_f32_dpp v26, v26, v26 row_half_mirror row_mask:0xf bank_mask:0xf bound_ctrl:1
	v_add_f32_dpp v27, v27, v27 row_half_mirror row_mask:0xf bank_mask:0xf bound_ctrl:1
	s_cmp_eq_u32 s21, 4
	v_add_f32_dpp v26, v26, v26 row_mirror row_mask:0xf bank_mask:0xf bound_ctrl:1
	v_add_f32_dpp v27, v27, v27 row_mirror row_mask:0xf bank_mask:0xf bound_ctrl:1
	s_cbranch_scc1 .Lml2_den4
.Lml2_back4:
	v_cvt_pk_bf16_f32 v28, v26, v27
	global_store_dword v4, v28, s[14:15] offset:-4096
	ds_read_b128 v[30:33], v58 offset:11264
	ds_read_b128 v[34:37], v58 offset:11520
	ds_read_b64 v[38:39], v59 offset:13824
	ds_read_b128 v[40:43], v60 offset:14688
	s_waitcnt lgkmcnt(4)
	v_pk_mul_f32 v[18:19], v[44:45], v[54:55] op_sel:[0,1] op_sel_hi:[1,1]
	v_pk_mul_f32 v[20:21], v[46:47], v[54:55] op_sel:[0,1] op_sel_hi:[1,1]
	v_pk_mul_f32 v[22:23], v[52:53], v[18:19] op_sel:[0,0] op_sel_hi:[1,0]
	v_pk_fma_f32 v[6:7], v[6:7], v[54:55], v[22:23] op_sel_hi:[1,0,1]
	v_pk_mul_f32 v[26:27], v[6:7], v[48:49] op_sel_hi:[1,0]
	v_pk_mul_f32 v[24:25], v[52:53], v[18:19] op_sel:[0,1] op_sel_hi:[1,1]
	v_pk_fma_f32 v[8:9], v[8:9], v[54:55], v[24:25] op_sel_hi:[1,0,1]
	v_pk_fma_f32 v[26:27], v[8:9], v[48:49], v[26:27] op_sel:[0,1,0] op_sel_hi:[1,1,1]
	v_pk_mul_f32 v[22:23], v[52:53], v[20:21] op_sel:[0,0] op_sel_hi:[1,0]
	v_pk_fma_f32 v[10:11], v[10:11], v[54:55], v[22:23] op_sel_hi:[1,0,1]
	v_pk_fma_f32 v[26:27], v[10:11], v[50:51], v[26:27] op_sel:[0,0,0] op_sel_hi:[1,0,1]
	v_pk_mul_f32 v[24:25], v[52:53], v[20:21] op_sel:[0,1] op_sel_hi:[1,1]
	v_pk_fma_f32 v[12:13], v[12:13], v[54:55], v[24:25] op_sel_hi:[1,0,1]
	v_pk_fma_f32 v[26:27], v[12:13], v[50:51], v[26:27] op_sel:[0,1,0] op_sel_hi:[1,1,1]
	v_pk_fma_f32 v[14:15], v[14:15], v[54:55], v[18:19] op_sel_hi:[1,0,1]
	v_pk_fma_f32 v[16:17], v[16:17], v[54:55], v[20:21] op_sel_hi:[1,0,1]
	v_add_f32_dpp v26, v26, v26 quad_perm:[1,0,3,2] row_mask:0xf bank_mask:0xf bound_ctrl:1
	v_add_f32_dpp v27, v27, v27 quad_perm:[1,0,3,2] row_mask:0xf bank_mask:0xf bound_ctrl:1
	s_add_u32 s14, s14, 0x1000
	v_add_f32_dpp v26, v26, v26 quad_perm:[2,3,0,1] row_mask:0xf bank_mask:0xf bound_ctrl:1
	v_add_f32_dpp v27, v27, v27 quad_perm:[2,3,0,1] row_mask:0xf bank_mask:0xf bound_ctrl:1
	s_addc_u32 s15, s15, 0
	v_add_f32_dpp v26, v26, v26 row_half_mirror row_mask:0xf bank_mask:0xf bound_ctrl:1
	v_add_f32_dpp v27, v27, v27 row_half_mirror row_mask:0xf bank_mask:0xf bound_ctrl:1
	s_cmp_eq_u32 s21, 5
	v_add_f32_dpp v26, v26, v26 row_mirror row_mask:0xf bank_mask:0xf bound_ctrl:1
	v_add_f32_dpp v27, v27, v27 row_mirror row_mask:0xf bank_mask:0xf bound_ctrl:1
	s_cbranch_scc1 .Lml2_den5
.Lml2_back5:
	v_cvt_pk_bf16_f32 v28, v26, v27
	global_store_dword v4, v28, s[14:15] offset:-4096
	ds_read_b128 v[44:47], v58 offset:11776
	ds_read_b128 v[48:51], v58 offset:12032
	ds_read_b64 v[52:53], v59 offset:14080
	ds_read_b128 v[54:57], v60 offset:14704
	s_waitcnt lgkmcnt(4)
	v_pk_mul_f32 v[18:19], v[30:31], v[40:41] op_sel:[0,1] op_sel_hi:[1,1]
	v_pk_mul_f32 v[20:21], v[32:33], v[40:41] op_sel:[0,1] op_sel_hi:[1,1]
	v_pk_mul_f32 v[22:23], v[38:39], v[18:19] op_sel:[0,0] op_sel_hi:[1,0]
	v_pk_fma_f32 v[6:7], v[6:7], v[40:41], v[22:23] op_sel_hi:[1,0,1]
	v_pk_mul_f32 v[26:27], v[6:7], v[34:35] op_sel_hi:[1,0]
	v_pk_mul_f32 v[24:25], v[38:39], v[18:19] op_sel:[0,1] op_sel_hi:[1,1]
	v_pk_fma_f32 v[8:9], v[8:9], v[40:41], v[24:25] op_sel_hi:[1,0,1]
	v_pk_fma_f32 v[26:27], v[8:9], v[34:35], v[26:27] op_sel:[0,1,0] op_sel_hi:[1,1,1]
	v_pk_mul_f32 v[22:23], v[38:39], v[20:21] op_sel:[0,0] op_sel_hi:[1,0]
	v_pk_fma_f32 v[10:11], v[10:11], v[40:41], v[22:23] op_sel_hi:[1,0,1]
	v_pk_fma_f32 v[26:27], v[10:11], v[36:37], v[26:27] op_sel:[0,0,0] op_sel_hi:[1,0,1]
	v_pk_mul_f32 v[24:25], v[38:39], v[20:21] op_sel:[0,1] op_sel_hi:[1,1]
	v_pk_fma_f32 v[12:13], v[12:13], v[40:41], v[24:25] op_sel_hi:[1,0,1]
	v_pk_fma_f32 v[26:27], v[12:13], v[36:37], v[26:27] op_sel:[0,1,0] op_sel_hi:[1,1,1]
	v_pk_fma_f32 v[14:15], v[14:15], v[40:41], v[18:19] op_sel_hi:[1,0,1]
	v_pk_fma_f32 v[16:17], v[16:17], v[40:41], v[20:21] op_sel_hi:[1,0,1]
	v_add_f32_dpp v26, v26, v26 quad_perm:[1,0,3,2] row_mask:0xf bank_mask:0xf bound_ctrl:1
	v_add_f32_dpp v27, v27, v27 quad_perm:[1,0,3,2] row_mask:0xf bank_mask:0xf bound_ctrl:1
	s_add_u32 s14, s14, 0x1000
	v_add_f32_dpp v26, v26, v26 quad_perm:[2,3,0,1] row_mask:0xf bank_mask:0xf bound_ctrl:1
	v_add_f32_dpp v27, v27, v27 quad_perm:[2,3,0,1] row_mask:0xf bank_mask:0xf bound_ctrl:1
	s_addc_u32 s15, s15, 0
	v_add_f32_dpp v26, v26, v26 row_half_mirror row_mask:0xf bank_mask:0xf bound_ctrl:1
	v_add_f32_dpp v27, v27, v27 row_half_mirror row_mask:0xf bank_mask:0xf bound_ctrl:1
	s_cmp_eq_u32 s21, 6
	v_add_f32_dpp v26, v26, v26 row_mirror row_mask:0xf bank_mask:0xf bound_ctrl:1
	v_add_f32_dpp v27, v27, v27 row_mirror row_mask:0xf bank_mask:0xf bound_ctrl:1
	s_cbranch_scc1 .Lml2_den6
.Lml2_back6:
	v_cvt_pk_bf16_f32 v28, v26, v27
	global_store_dword v4, v28, s[14:15] offset:-4096
	ds_read_b128 v[30:33], v61 offset:8192
	ds_read_b128 v[34:37], v61 offset:8448
	ds_read_b64 v[38:39], v62 offset:12288
	ds_read_b128 v[40:43], v63 offset:14592
	s_waitcnt lgkmcnt(4)
	v_pk_mul_f32 v[18:19], v[44:45], v[54:55] op_sel:[0,1] op_sel_hi:[1,1]
	v_pk_mul_f32 v[20:21], v[46:47], v[54:55] op_sel:[0,1] op_sel_hi:[1,1]
	v_pk_mul_f32 v[22:23], v[52:53], v[18:19] op_sel:[0,0] op_sel_hi:[1,0]
	v_pk_fma_f32 v[6:7], v[6:7], v[54:55], v[22:23] op_sel_hi:[1,0,1]
	v_pk_mul_f32 v[26:27], v[6:7], v[48:49] op_sel_hi:[1,0]
	v_pk_mul_f32 v[24:25], v[52:53], v[18:19] op_sel:[0,1] op_sel_hi:[1,1]
	v_pk_fma_f32 v[8:9], v[8:9], v[54:55], v[24:25] op_sel_hi:[1,0,1]
	v_pk_fma_f32 v[26:27], v[8:9], v[48:49], v[26:27] op_sel:[0,1,0] op_sel_hi:[1,1,1]
	v_pk_mul_f32 v[22:23], v[52:53], v[20:21] op_sel:[0,0] op_sel_hi:[1,0]
	v_pk_fma_f32 v[10:11], v[10:11], v[54:55], v[22:23] op_sel_hi:[1,0,1]
	v_pk_fma_f32 v[26:27], v[10:11], v[50:51], v[26:27] op_sel:[0,0,0] op_sel_hi:[1,0,1]
	v_pk_mul_f32 v[24:25], v[52:53], v[20:21] op_sel:[0,1] op_sel_hi:[1,1]
	v_pk_fma_f32 v[12:13], v[12:13], v[54:55], v[24:25] op_sel_hi:[1,0,1]
	v_pk_fma_f32 v[26:27], v[12:13], v[50:51], v[26:27] op_sel:[0,1,0] op_sel_hi:[1,1,1]
	v_pk_fma_f32 v[14:15], v[14:15], v[54:55], v[18:19] op_sel_hi:[1,0,1]
	v_pk_fma_f32 v[16:17], v[16:17], v[54:55], v[20:21] op_sel_hi:[1,0,1]
	v_add_f32_dpp v26, v26, v26 quad_perm:[1,0,3,2] row_mask:0xf bank_mask:0xf bound_ctrl:1
	v_add_f32_dpp v27, v27, v27 quad_perm:[1,0,3,2] row_mask:0xf bank_mask:0xf bound_ctrl:1
	s_add_u32 s14, s14, 0x1000
	v_add_f32_dpp v26, v26, v26 quad_perm:[2,3,0,1] row_mask:0xf bank_mask:0xf bound_ctrl:1
	v_add_f32_dpp v27, v27, v27 quad_perm:[2,3,0,1] row_mask:0xf bank_mask:0xf bound_ctrl:1
	s_addc_u32 s15, s15, 0
	v_add_f32_dpp v26, v26, v26 row_half_mirror row_mask:0xf bank_mask:0xf bound_ctrl:1
	v_add_f32_dpp v27, v27, v27 row_half_mirror row_mask:0xf bank_mask:0xf bound_ctrl:1
	s_cmp_eq_u32 s21, 7
	v_add_f32_dpp v26, v26, v26 row_mirror row_mask:0xf bank_mask:0xf bound_ctrl:1
	v_add_f32_dpp v27, v27, v27 row_mirror row_mask:0xf bank_mask:0xf bound_ctrl:1
	s_cbranch_scc1 .Lml2_den7
.Lml2_back7:
	v_cvt_pk_bf16_f32 v28, v26, v27
	global_store_dword v4, v28, s[14:15] offset:-4096
	s_waitcnt vmcnt(8)
	v_lshlrev_b32_e32 v88, 16, v80
	v_lshlrev_b32_e32 v89, 16, v81
	v_and_b32_e32 v90, s17, v80
	v_and_b32_e32 v91, s17, v81
	v_lshlrev_b32_e32 v92, 16, v82
	v_and_b32_e32 v93, s17, v82
	v_lshlrev_b32_e32 v94, 16, v83
	v_and_b32_e32 v95, s17, v83
	v_lshlrev_b32_e32 v96, 16, v84
	v_and_b32_e32 v97, s17, v84
	ds_write_b128 v64, v[88:91]
	ds_write_b64 v65, v[92:93]
	ds_write_b64 v66, v[94:95]
	ds_write_b64 v66, v[96:97] offset:128
	ds_write_b32 v67, v85
	s_cmp_lg_u32 s36, 4
	s_cbranch_scc1 .Lml2_nsc2
	v_mov_b32_e32 v98, v87
	s_nop 1
	v_add_f32_dpp v98, v98, v98 row_shr:1 row_mask:0xf bank_mask:0xf bound_ctrl:1
	s_nop 1
	v_add_f32_dpp v98, v98, v98 row_shr:2 row_mask:0xf bank_mask:0xf bound_ctrl:1
	s_nop 1
	v_add_f32_dpp v98, v98, v98 row_shr:4 row_mask:0xf bank_mask:0xf bound_ctrl:1
	s_nop 1
	v_sub_f32_e32 v99, v86, v98
	s_nop 1
	v_max_f32_dpp v99, v99, v99 row_shr:1 row_mask:0xf bank_mask:0xf
	s_nop 1
	v_max_f32_dpp v99, v99, v99 row_shr:2 row_mask:0xf bank_mask:0xf
	s_nop 1
	v_max_f32_dpp v99, v99, v99 row_shr:4 row_mask:0xf bank_mask:0xf
	s_nop 1
	v_max_f32_e32 v99, v99, v0
	v_add_f32_e32 v103, v98, v99
	v_mov_b32_e32 v105, v0
	s_nop 0
	v_mov_b32_dpp v105, v103 row_shr:1 row_mask:0xf bank_mask:0xf
	v_sub_f32_e32 v104, v86, v103
	v_add_f32_e32 v105, v87, v105
	v_fma_f32 v104, v104, s29, v29
	v_sub_f32_e32 v105, v105, v103
	v_exp_f32_e32 v101, v104
	v_mul_f32_e32 v105, s29, v105
	v_mul_f32_e32 v104, 0xbfb8aa3b, v103
	v_exp_f32_e32 v100, v105
	v_exp_f32_e32 v102, v104
	v_readlane_b32 s4, v103, 7
	s_nop 3
	v_mov_b32_e32 v0, s4
	ds_write_b128 v68, v[100:103]
.Lml2_nsc2:
	s_mov_b32 s0, s18
	s_mov_b32 s18, s19
	s_mov_b32 s19, s20
	s_mov_b32 s20, s0
	v_mov_b32_e32 v58, v61
	v_mov_b32_e32 v59, v62
	v_mov_b32_e32 v60, v63
	v_add_u32_e32 v61, s19, v2
	v_add_u32_e32 v62, s19, v3
	v_mov_b32_e32 v63, s19
	v_add_u32_e32 v64, s20, v69
	v_add_u32_e32 v65, s20, v70
	v_add_u32_e32 v66, s20, v71
	v_add_u32_e32 v67, s20, v72
	v_add_u32_e32 v68, s20, v73
	s_add_u32 s24, s24, 0x400
	s_addc_u32 s25, s25, 0
	s_sub_i32 s21, s21, 8
	s_add_i32 s16, s16, 8
	s_waitcnt lgkmcnt(0)
	s_barrier
	s_cmpk_lt_u32 s16, 0x800
	s_cbranch_scc1 .Lml2_loop
	s_lshr_b32 s2, s30, 4
	s_lshl_b32 s4, s2, 15
	s_add_u32 s4, s4, 0x44c8000
	s_add_u32 s0, s34, s4
	s_addc_u32 s1, s35, 0
	v_and_b32_e32 v104, 15, v198
	v_lshlrev_b32_e32 v105, 11, v104
	v_lshl_add_u32 v105, v4, 1, v105
	global_store_dwordx2 v105, v[6:7], s[0:1] offset:0
	global_store_dwordx2 v105, v[8:9], s[0:1] offset:512
	global_store_dwordx2 v105, v[10:11], s[0:1] offset:1024
	global_store_dwordx2 v105, v[12:13], s[0:1] offset:1536
	s_cmp_lg_u32 s31, 0
	s_cbranch_scc1 .Lml2_nonm
	s_lshl_b32 s4, s2, 8
	s_add_u32 s4, s4, 0x46c8000
	s_add_u32 s0, s34, s4
	s_addc_u32 s1, s35, 0
	v_lshlrev_b32_e32 v104, 4, v104
	global_store_dwordx2 v104, v[14:15], s[0:1]
	global_store_dwordx2 v104, v[16:17], s[0:1] offset:8
	s_lshl_b32 s4, s2, 2
	s_add_u32 s4, s4, 0x46cc000
	s_add_u32 s0, s34, s4
	s_addc_u32 s1, s35, 0
	global_store_dword v1, v57, s[0:1]

.Lml2_den0:
	v_pk_mul_f32 v[22:23], v[14:15], v[34:35]
	v_pk_fma_f32 v[22:23], v[16:17], v[36:37], v[22:23]
	s_nop 0
	v_add_f32_e32 v22, v22, v23
	s_nop 1
	v_add_f32_dpp v22, v22, v22 quad_perm:[1,0,3,2] row_mask:0xf bank_mask:0xf bound_ctrl:1
	s_nop 1
	v_add_f32_dpp v22, v22, v22 quad_perm:[2,3,0,1] row_mask:0xf bank_mask:0xf bound_ctrl:1
	s_nop 1
	v_add_f32_dpp v22, v22, v22 row_half_mirror row_mask:0xf bank_mask:0xf bound_ctrl:1
	s_nop 1
	v_add_f32_dpp v22, v22, v22 row_mirror row_mask:0xf bank_mask:0xf bound_ctrl:1
	v_max_f32_e64 v22, |v22|, v42
	v_rcp_f32_e32 v22, v22
	s_add_i32 s21, s21, 16
	global_store_dword v1, v22, s[24:25] offset:8
	s_branch .Lml2_back0
.Lml2_den1:
	v_pk_mul_f32 v[22:23], v[14:15], v[48:49]
	v_pk_fma_f32 v[22:23], v[16:17], v[50:51], v[22:23]
	s_nop 0
	v_add_f32_e32 v22, v22, v23
	s_nop 1
	v_add_f32_dpp v22, v22, v22 quad_perm:[1,0,3,2] row_mask:0xf bank_mask:0xf bound_ctrl:1
	s_nop 1
	v_add_f32_dpp v22, v22, v22 quad_perm:[2,3,0,1] row_mask:0xf bank_mask:0xf bound_ctrl:1
	s_nop 1
	v_add_f32_dpp v22, v22, v22 row_half_mirror row_mask:0xf bank_mask:0xf bound_ctrl:1
	s_nop 1
	v_add_f32_dpp v22, v22, v22 row_mirror row_mask:0xf bank_mask:0xf bound_ctrl:1
	v_max_f32_e64 v22, |v22|, v56
	v_rcp_f32_e32 v22, v22
	s_add_i32 s21, s21, 16
	global_store_dword v1, v22, s[24:25] offset:136
	s_branch .Lml2_back1
.Lml2_den2:
	v_pk_mul_f32 v[22:23], v[14:15], v[34:35]
	v_pk_fma_f32 v[22:23], v[16:17], v[36:37], v[22:23]
	s_nop 0
	v_add_f32_e32 v22, v22, v23
	s_nop 1
	v_add_f32_dpp v22, v22, v22 quad_perm:[1,0,3,2] row_mask:0xf bank_mask:0xf bound_ctrl:1
	s_nop 1
	v_add_f32_dpp v22, v22, v22 quad_perm:[2,3,0,1] row_mask:0xf bank_mask:0xf bound_ctrl:1
	s_nop 1
	v_add_f32_dpp v22, v22, v22 row_half_mirror row_mask:0xf bank_mask:0xf bound_ctrl:1
	s_nop 1
	v_add_f32_dpp v22, v22, v22 row_mirror row_mask:0xf bank_mask:0xf bound_ctrl:1
	v_max_f32_e64 v22, |v22|, v42
	v_rcp_f32_e32 v22, v22
	s_add_i32 s21, s21, 16
	global_store_dword v1, v22, s[24:25] offset:264
	s_branch .Lml2_back2
.Lml2_den3:
	v_pk_mul_f32 v[22:23], v[14:15], v[48:49]
	v_pk_fma_f32 v[22:23], v[16:17], v[50:51], v[22:23]
	s_nop 0
	v_add_f32_e32 v22, v22, v23
	s_nop 1
	v_add_f32_dpp v22, v22, v22 quad_perm:[1,0,3,2] row_mask:0xf bank_mask:0xf bound_ctrl:1
	s_nop 1
	v_add_f32_dpp v22, v22, v22 quad_perm:[2,3,0,1] row_mask:0xf bank_mask:0xf bound_ctrl:1
	s_nop 1
	v_add_f32_dpp v22, v22, v22 row_half_mirror row_mask:0xf bank_mask:0xf bound_ctrl:1
	s_nop 1
	v_add_f32_dpp v22, v22, v22 row_mirror row_mask:0xf bank_mask:0xf bound_ctrl:1
	v_max_f32_e64 v22, |v22|, v56
	v_rcp_f32_e32 v22, v22
	s_add_i32 s21, s21, 16
	global_store_dword v1, v22, s[24:25] offset:392
	s_branch .Lml2_back3
.Lml2_den4:
	v_pk_mul_f32 v[22:23], v[14:15], v[34:35]
	v_pk_fma_f32 v[22:23], v[16:17], v[36:37], v[22:23]
	s_nop 0
	v_add_f32_e32 v22, v22, v23
	s_nop 1
	v_add_f32_dpp v22, v22, v22 quad_perm:[1,0,3,2] row_mask:0xf bank_mask:0xf bound_ctrl:1
	s_nop 1
	v_add_f32_dpp v22, v22, v22 quad_perm:[2,3,0,1] row_mask:0xf bank_mask:0xf bound_ctrl:1
	s_nop 1
	v_add_f32_dpp v22, v22, v22 row_half_mirror row_mask:0xf bank_mask:0xf bound_ctrl:1
	s_nop 1
	v_add_f32_dpp v22, v22, v22 row_mirror row_mask:0xf bank_mask:0xf bound_ctrl:1
	v_max_f32_e64 v22, |v22|, v42
	v_rcp_f32_e32 v22, v22
	s_add_i32 s21, s21, 16
	global_store_dword v1, v22, s[24:25] offset:520
	s_branch .Lml2_back4
.Lml2_den5:
	v_pk_mul_f32 v[22:23], v[14:15], v[48:49]
	v_pk_fma_f32 v[22:23], v[16:17], v[50:51], v[22:23]
	s_nop 0
	v_add_f32_e32 v22, v22, v23
	s_nop 1
	v_add_f32_dpp v22, v22, v22 quad_perm:[1,0,3,2] row_mask:0xf bank_mask:0xf bound_ctrl:1
	s_nop 1
	v_add_f32_dpp v22, v22, v22 quad_perm:[2,3,0,1] row_mask:0xf bank_mask:0xf bound_ctrl:1
	s_nop 1
	v_add_f32_dpp v22, v22, v22 row_half_mirror row_mask:0xf bank_mask:0xf bound_ctrl:1
	s_nop 1
	v_add_f32_dpp v22, v22, v22 row_mirror row_mask:0xf bank_mask:0xf bound_ctrl:1
	v_max_f32_e64 v22, |v22|, v56
	v_rcp_f32_e32 v22, v22
	s_add_i32 s21, s21, 16
	global_store_dword v1, v22, s[24:25] offset:648
	s_branch .Lml2_back5
.Lml2_den6:
	v_pk_mul_f32 v[22:23], v[14:15], v[34:35]
	v_pk_fma_f32 v[22:23], v[16:17], v[36:37], v[22:23]
	s_nop 0
	v_add_f32_e32 v22, v22, v23
	s_nop 1
	v_add_f32_dpp v22, v22, v22 quad_perm:[1,0,3,2] row_mask:0xf bank_mask:0xf bound_ctrl:1
	s_nop 1
	v_add_f32_dpp v22, v22, v22 quad_perm:[2,3,0,1] row_mask:0xf bank_mask:0xf bound_ctrl:1
	s_nop 1
	v_add_f32_dpp v22, v22, v22 row_half_mirror row_mask:0xf bank_mask:0xf bound_ctrl:1
	s_nop 1
	v_add_f32_dpp v22, v22, v22 row_mirror row_mask:0xf bank_mask:0xf bound_ctrl:1
	v_max_f32_e64 v22, |v22|, v42
	v_rcp_f32_e32 v22, v22
	s_add_i32 s21, s21, 16
	global_store_dword v1, v22, s[24:25] offset:776
	s_branch .Lml2_back6
.Lml2_den7:
	v_pk_mul_f32 v[22:23], v[14:15], v[48:49]
	v_pk_fma_f32 v[22:23], v[16:17], v[50:51], v[22:23]
	s_nop 0
	v_add_f32_e32 v22, v22, v23
	s_nop 1
	v_add_f32_dpp v22, v22, v22 quad_perm:[1,0,3,2] row_mask:0xf bank_mask:0xf bound_ctrl:1
	s_nop 1
	v_add_f32_dpp v22, v22, v22 quad_perm:[2,3,0,1] row_mask:0xf bank_mask:0xf bound_ctrl:1
	s_nop 1
	v_add_f32_dpp v22, v22, v22 row_half_mirror row_mask:0xf bank_mask:0xf bound_ctrl:1
	s_nop 1
	v_add_f32_dpp v22, v22, v22 row_mirror row_mask:0xf bank_mask:0xf bound_ctrl:1
	v_max_f32_e64 v22, |v22|, v56
	v_rcp_f32_e32 v22, v22
	s_add_i32 s21, s21, 16
	global_store_dword v1, v22, s[24:25] offset:904
	s_branch .Lml2_back7

.LBB0_186:
	s_andn2_b64 vcc, exec, s[0:1]
	s_cbranch_vccnz .LBB0_232
	s_and_b64 vcc, exec, s[6:7]
	s_cbranch_vccnz .LBB0_232
	v_readlane_b32 s0, v255, 18
	v_readlane_b32 s1, v255, 19
	s_load_dwordx2 s[24:25], s[0:1], 0xe8
	s_load_dwordx2 s[22:23], s[0:1], 0xf0
	v_readlane_b32 s5, v255, 15
	v_and_b32_e32 v155, 15, v198
	v_lshrrev_b32_e32 v5, 4, v198
	v_lshlrev_b32_e32 v2, 4, v155
	v_lshlrev_b32_e32 v4, 12, v155
	s_mov_b32 s17, 0xffff0000
	v_and_b32_e32 v155, 3, v198
	v_lshrrev_b32_e32 v156, 2, v198
	v_lshlrev_b32_e32 v32, 8, v155
	v_lshl_add_u32 v32, v156, 4, v32
	s_lshl_b32 s0, s5, 10
	s_add_u32 s0, s0, 0
	v_add_u32_e32 v32, s0, v32
	s_lshl_b32 s0, s5, 9
	s_add_u32 s0, s0, 8192
	v_lshl_add_u32 v33, v198, 3, s0
	v_min_u32_e32 v155, 15, v198
	s_lshl_b32 s0, s5, 8
	s_add_u32 s0, s0, 12288
	v_lshl_add_u32 v34, v155, 3, s0
	v_min_u32_e32 v156, 2, v198
	v_lshlrev_b32_e32 v106, 2, v156
	s_lshl_b32 s0, s5, 4
	s_add_u32 s0, s0, 14336
	v_add_u32_e32 v35, s0, v106
	v_lshlrev_b32_e32 v36, 2, v198
	v_and_b32_e32 v156, 31, v198
	v_lshlrev_b32_e32 v37, 2, v156
	v_cmp_gt_u32_e32 vcc, 32, v198
	v_add_u32_e32 v156, 1024, v37
	s_nop 1
	v_cndmask_b32_e32 v37, v37, v156, vcc
	s_waitcnt lgkmcnt(0)
.Lgd2_item:
	s_lshr_b32 s2, s27, 4
	s_and_b32 s3, s27, 15
	s_lshl_b32 s4, s3, 4
	v_lshl_add_u32 v154, v5, 2, s4
	v_lshl_add_u32 v153, v154, 1, v4
	s_and_b32 s4, s3, 3
	s_lshl_b32 s4, s4, 5
	v_lshl_add_u32 v3, v5, 3, s4
	s_and_b32 s4, s3, 12
	s_lshl_b32 s4, s4, 4
	v_min_u32_e32 v155, 15, v198
	v_lshl_add_u32 v104, v155, 2, s4
	s_and_b32 s5, s2, 7
	s_lshl_b32 s3, s5, 7
	s_add_u32 s4, s4, s3
	s_add_u32 s4, s4, 2048
	v_lshl_add_u32 v105, v155, 2, s4
	s_lshr_b32 s4, s2, 3
	v_readlane_b32 s3, v255, 15
	s_mul_i32 s6, s4, 0xc00000
	s_mul_i32 s7, s3, 0x1800
	s_add_u32 s6, s6, s7
	s_lshl_b32 s7, s5, 8
	s_add_u32 s6, s6, s7
	s_add_u32 s6, s6, 0xb38d900
	s_add_u32 s8, s24, s6
	s_addc_u32 s9, s25, 0
	s_lshl_b32 s6, s4, 25
	s_lshl_b32 s7, s3, 14
	s_add_u32 s6, s6, s7
	s_lshl_b32 s7, s5, 7
	s_add_u32 s6, s6, s7
	s_add_u32 s6, s6, 62659584
	s_add_u32 s10, s22, s6
	s_addc_u32 s11, s23, 0
	s_lshl_b32 s6, s4, 18
	s_lshl_b32 s7, s3, 7
	s_add_u32 s6, s6, s7
	s_lshl_b32 s7, s5, 4
	s_add_u32 s6, s6, s7
	s_add_u32 s6, s6, 0x37b8400
	s_add_u32 s12, s22, s6
	s_addc_u32 s13, s23, 0
	s_lshl_b32 s6, s4, 23
	s_lshl_b32 s7, s5, 8
	s_add_u32 s6, s6, s7
	s_add_u32 s6, s6, 333186048
	s_add_u32 s14, s22, s6
	s_addc_u32 s15, s23, 0
	s_movk_i32 s18, 256
	s_movk_i32 s19, 16640
	s_mov_b32 s20, 33024
	v_add_u32_e32 v28, s18, v32
	v_add_u32_e32 v29, s18, v33
	v_add_u32_e32 v30, s18, v34
	v_add_u32_e32 v31, s18, v35
	global_load_dword v108, v36, s[8:9]
	global_load_dword v109, v36, s[8:9] offset:-2048
	global_load_dword v111, v104, s[8:9] offset:2048
	global_load_dword v110, v37, s[10:11]
	global_load_dword v112, v105, s[10:11]
	global_load_dword v113, v106, s[12:13]
	s_add_u32 s8, s8, 0xc000
	s_addc_u32 s9, s9, 0
	s_add_u32 s10, s10, 0x20000
	s_addc_u32 s11, s11, 0
	s_add_u32 s12, s12, 0x400
	s_addc_u32 s13, s13, 0
	s_waitcnt vmcnt(0)
	v_lshlrev_b32_e32 v116, 16, v108
	v_lshlrev_b32_e32 v117, 16, v109
	v_and_b32_e32 v118, s17, v108
	v_and_b32_e32 v119, s17, v109
	v_lshlrev_b32_e32 v120, 16, v110
	v_and_b32_e32 v121, s17, v110
	v_lshlrev_b32_e32 v122, 16, v111
	v_and_b32_e32 v123, s17, v111
	v_lshlrev_b32_e32 v124, 16, v112
	v_and_b32_e32 v125, s17, v112
	ds_write_b128 v28, v[116:119]
	ds_write_b64 v29, v[120:121]
	ds_write_b64 v30, v[122:123]
	ds_write_b64 v30, v[124:125] offset:128
	ds_write_b32 v31, v113
	v_add_u32_e32 v28, s19, v32
	v_add_u32_e32 v29, s19, v33
	v_add_u32_e32 v30, s19, v34
	v_add_u32_e32 v31, s19, v35
	global_load_dword v108, v36, s[8:9]
	global_load_dword v109, v36, s[8:9] offset:-2048
	global_load_dword v111, v104, s[8:9] offset:2048
	global_load_dword v110, v37, s[10:11]
	global_load_dword v112, v105, s[10:11]
	global_load_dword v113, v106, s[12:13]
	s_add_u32 s8, s8, 0xc000
	s_addc_u32 s9, s9, 0
	s_add_u32 s10, s10, 0x20000
	s_addc_u32 s11, s11, 0
	s_add_u32 s12, s12, 0x400
	s_addc_u32 s13, s13, 0
	s_waitcnt vmcnt(0)
	v_lshlrev_b32_e32 v116, 16, v108
	v_lshlrev_b32_e32 v117, 16, v109
	v_and_b32_e32 v118, s17, v108
	v_and_b32_e32 v119, s17, v109
	v_lshlrev_b32_e32 v120, 16, v110
	v_and_b32_e32 v121, s17, v110
	v_lshlrev_b32_e32 v122, 16, v111
	v_and_b32_e32 v123, s17, v111
	v_lshlrev_b32_e32 v124, 16, v112
	v_and_b32_e32 v125, s17, v112
	ds_write_b128 v28, v[116:119]
	ds_write_b64 v29, v[120:121]
	ds_write_b64 v30, v[122:123]
	ds_write_b64 v30, v[124:125] offset:128
	ds_write_b32 v31, v113
	v_add_u32_e32 v28, s20, v32
	v_add_u32_e32 v29, s20, v33
	v_add_u32_e32 v30, s20, v34
	v_add_u32_e32 v31, s20, v35
	v_add_u32_e32 v22, s18, v2
	v_add_u32_e32 v23, s18, v3
	v_mov_b32_e32 v24, s18
	v_add_u32_e32 v25, s19, v2
	v_add_u32_e32 v26, s19, v3
	v_mov_b32_e32 v27, s19
	v_mov_b32_e32 v6, 0
	v_mov_b32_e32 v7, 0
	v_mov_b32_e32 v8, 0
	v_mov_b32_e32 v9, 0
	v_mov_b32_e32 v10, 0
	v_mov_b32_e32 v11, 0
	v_mov_b32_e32 v12, 0
	v_mov_b32_e32 v13, 0
	v_mov_b32_e32 v14, 0
	v_mov_b32_e32 v15, 0
	v_mov_b32_e32 v16, 0
	v_mov_b32_e32 v17, 0
	v_mov_b32_e32 v18, 0
	v_mov_b32_e32 v19, 0
	v_mov_b32_e32 v20, 0
	v_mov_b32_e32 v21, 0
	v_mov_b32_e32 v51, 1.0
	s_mov_b32 s16, 0
	s_waitcnt vmcnt(0) lgkmcnt(0)
	s_barrier
	s_setprio 1
	ds_read_b128 v[56:59], v22 offset:0
	ds_read_b128 v[60:63], v22 offset:256
	ds_read_b128 v[64:67], v22 offset:512
	ds_read_b128 v[68:71], v22 offset:768
	ds_read_b64 v[72:73], v23 offset:12288
	ds_read_b128 v[76:79], v24 offset:14336
.Lgd2_loop:
	global_load_dword v108, v36, s[8:9]
	global_load_dword v109, v36, s[8:9] offset:-2048
	global_load_dword v111, v104, s[8:9] offset:2048
	global_load_dword v110, v37, s[10:11]
	global_load_dword v112, v105, s[10:11]
	global_load_dword v113, v106, s[12:13]
	s_add_u32 s8, s8, 0xc000
	s_addc_u32 s9, s9, 0
	s_add_u32 s10, s10, 0x20000
	s_addc_u32 s11, s11, 0
	s_add_u32 s12, s12, 0x400
	s_addc_u32 s13, s13, 0
	ds_read_b128 v[80:83], v22 offset:1024
	ds_read_b128 v[84:87], v22 offset:1280
	ds_read_b128 v[88:91], v22 offset:1536
	ds_read_b128 v[92:95], v22 offset:1792
	ds_read_b64 v[96:97], v23 offset:12544
	ds_read_b128 v[100:103], v24 offset:14352
	s_waitcnt lgkmcnt(6)
	v_pk_mul_f32 v[38:39], v[6:7], v[56:57] op_sel_hi:[1,0]
	v_pk_mul_f32 v[40:41], v[6:7], v[56:57] op_sel:[0,1] op_sel_hi:[1,1]
	v_pk_fma_f32 v[38:39], v[8:9], v[58:59], v[38:39] op_sel_hi:[1,0,1]
	v_pk_fma_f32 v[40:41], v[8:9], v[58:59], v[40:41] op_sel:[0,1,0] op_sel_hi:[1,1,1]
	v_pk_fma_f32 v[38:39], v[10:11], v[60:61], v[38:39] op_sel_hi:[1,0,1]
	v_pk_fma_f32 v[40:41], v[10:11], v[60:61], v[40:41] op_sel:[0,1,0] op_sel_hi:[1,1,1]
	v_pk_fma_f32 v[38:39], v[12:13], v[62:63], v[38:39] op_sel_hi:[1,0,1]
	v_pk_fma_f32 v[40:41], v[12:13], v[62:63], v[40:41] op_sel:[0,1,0] op_sel_hi:[1,1,1]
	v_pk_fma_f32 v[38:39], v[14:15], v[64:65], v[38:39] op_sel_hi:[1,0,1]
	v_pk_fma_f32 v[40:41], v[14:15], v[64:65], v[40:41] op_sel:[0,1,0] op_sel_hi:[1,1,1]
	v_pk_fma_f32 v[38:39], v[16:17], v[66:67], v[38:39] op_sel_hi:[1,0,1]
	v_pk_fma_f32 v[40:41], v[16:17], v[66:67], v[40:41] op_sel:[0,1,0] op_sel_hi:[1,1,1]
	v_pk_fma_f32 v[38:39], v[18:19], v[68:69], v[38:39] op_sel_hi:[1,0,1]
	v_pk_fma_f32 v[40:41], v[18:19], v[68:69], v[40:41] op_sel:[0,1,0] op_sel_hi:[1,1,1]
	v_pk_fma_f32 v[38:39], v[20:21], v[70:71], v[38:39] op_sel_hi:[1,0,1]
	v_pk_fma_f32 v[40:41], v[20:21], v[70:71], v[40:41] op_sel:[0,1,0] op_sel_hi:[1,1,1]
	v_mul_f32_e32 v50, v76, v51
	v_add_f32_dpp v38, v38, v38 quad_perm:[1,0,3,2] row_mask:0xf bank_mask:0xf bound_ctrl:1
	v_add_f32_dpp v39, v39, v39 quad_perm:[1,0,3,2] row_mask:0xf bank_mask:0xf bound_ctrl:1
	v_add_f32_dpp v40, v40, v40 quad_perm:[1,0,3,2] row_mask:0xf bank_mask:0xf bound_ctrl:1
	v_add_f32_dpp v41, v41, v41 quad_perm:[1,0,3,2] row_mask:0xf bank_mask:0xf bound_ctrl:1
	v_add_f32_dpp v38, v38, v38 quad_perm:[2,3,0,1] row_mask:0xf bank_mask:0xf bound_ctrl:1
	v_add_f32_dpp v39, v39, v39 quad_perm:[2,3,0,1] row_mask:0xf bank_mask:0xf bound_ctrl:1
	v_add_f32_dpp v40, v40, v40 quad_perm:[2,3,0,1] row_mask:0xf bank_mask:0xf bound_ctrl:1
	v_add_f32_dpp v41, v41, v41 quad_perm:[2,3,0,1] row_mask:0xf bank_mask:0xf bound_ctrl:1
	v_add_f32_dpp v38, v38, v38 row_half_mirror row_mask:0xf bank_mask:0xf bound_ctrl:1
	v_add_f32_dpp v39, v39, v39 row_half_mirror row_mask:0xf bank_mask:0xf bound_ctrl:1
	v_add_f32_dpp v40, v40, v40 row_half_mirror row_mask:0xf bank_mask:0xf bound_ctrl:1
	v_add_f32_dpp v41, v41, v41 row_half_mirror row_mask:0xf bank_mask:0xf bound_ctrl:1
	v_add_f32_dpp v38, v38, v38 row_mirror row_mask:0xf bank_mask:0xf bound_ctrl:1
	v_add_f32_dpp v39, v39, v39 row_mirror row_mask:0xf bank_mask:0xf bound_ctrl:1
	v_add_f32_dpp v40, v40, v40 row_mirror row_mask:0xf bank_mask:0xf bound_ctrl:1
	v_add_f32_dpp v41, v41, v41 row_mirror row_mask:0xf bank_mask:0xf bound_ctrl:1
	v_cmp_gt_f32_e32 vcc, 0x2b8cbccc, v50
	v_pk_fma_f32 v[44:45], v[38:39], v[50:51], v[72:73] op_sel:[0,0,0] op_sel_hi:[1,0,1] neg_lo:[1,0,0] neg_hi:[1,0,0]
	v_pk_mul_f32 v[44:45], v[44:45], v[76:77] op_sel:[0,1] op_sel_hi:[1,1]
	v_pk_mul_f32 v[48:49], v[44:45], v[78:79] op_sel_hi:[1,0]
	v_pk_fma_f32 v[48:49], v[40:41], v[50:51], v[48:49] op_sel:[0,0,0] op_sel_hi:[1,0,1]
	s_cbranch_vccnz .Lgd2_rare0
.Lgd2_back0:
	v_rcp_f32_e32 v52, v50
	v_cvt_pk_bf16_f32 v54, v48, v49
	v_pk_mul_f32 v[46:47], v[44:45], v[52:53] op_sel_hi:[1,0]
	v_pk_fma_f32 v[6:7], v[56:57], v[46:47], v[6:7] op_sel_hi:[0,1,1]
	v_pk_fma_f32 v[8:9], v[58:59], v[46:47], v[8:9] op_sel_hi:[0,1,1]
	v_pk_fma_f32 v[10:11], v[60:61], v[46:47], v[10:11] op_sel_hi:[0,1,1]
	v_pk_fma_f32 v[12:13], v[62:63], v[46:47], v[12:13] op_sel_hi:[0,1,1]
	v_pk_fma_f32 v[14:15], v[64:65], v[46:47], v[14:15] op_sel_hi:[0,1,1]
	v_pk_fma_f32 v[16:17], v[66:67], v[46:47], v[16:17] op_sel_hi:[0,1,1]
	v_pk_fma_f32 v[18:19], v[68:69], v[46:47], v[18:19] op_sel_hi:[0,1,1]
	v_pk_fma_f32 v[20:21], v[70:71], v[46:47], v[20:21] op_sel_hi:[0,1,1]
	global_store_dword v154, v54, s[14:15]
	s_add_u32 s14, s14, 0x1000
	s_addc_u32 s15, s15, 0
	ds_read_b128 v[56:59], v22 offset:2048
	ds_read_b128 v[60:63], v22 offset:2304
	ds_read_b128 v[64:67], v22 offset:2560
	ds_read_b128 v[68:71], v22 offset:2816
	ds_read_b64 v[72:73], v23 offset:12800
	ds_read_b128 v[76:79], v24 offset:14368
	s_waitcnt lgkmcnt(6)
	v_pk_mul_f32 v[38:39], v[6:7], v[80:81] op_sel_hi:[1,0]
	v_pk_mul_f32 v[40:41], v[6:7], v[80:81] op_sel:[0,1] op_sel_hi:[1,1]
	v_pk_fma_f32 v[38:39], v[8:9], v[82:83], v[38:39] op_sel_hi:[1,0,1]
	v_pk_fma_f32 v[40:41], v[8:9], v[82:83], v[40:41] op_sel:[0,1,0] op_sel_hi:[1,1,1]
	v_pk_fma_f32 v[38:39], v[10:11], v[84:85], v[38:39] op_sel_hi:[1,0,1]
	v_pk_fma_f32 v[40:41], v[10:11], v[84:85], v[40:41] op_sel:[0,1,0] op_sel_hi:[1,1,1]
	v_pk_fma_f32 v[38:39], v[12:13], v[86:87], v[38:39] op_sel_hi:[1,0,1]
	v_pk_fma_f32 v[40:41], v[12:13], v[86:87], v[40:41] op_sel:[0,1,0] op_sel_hi:[1,1,1]
	v_pk_fma_f32 v[38:39], v[14:15], v[88:89], v[38:39] op_sel_hi:[1,0,1]
	v_pk_fma_f32 v[40:41], v[14:15], v[88:89], v[40:41] op_sel:[0,1,0] op_sel_hi:[1,1,1]
	v_pk_fma_f32 v[38:39], v[16:17], v[90:91], v[38:39] op_sel_hi:[1,0,1]
	v_pk_fma_f32 v[40:41], v[16:17], v[90:91], v[40:41] op_sel:[0,1,0] op_sel_hi:[1,1,1]
	v_pk_fma_f32 v[38:39], v[18:19], v[92:93], v[38:39] op_sel_hi:[1,0,1]
	v_pk_fma_f32 v[40:41], v[18:19], v[92:93], v[40:41] op_sel:[0,1,0] op_sel_hi:[1,1,1]
	v_pk_fma_f32 v[38:39], v[20:21], v[94:95], v[38:39] op_sel_hi:[1,0,1]
	v_pk_fma_f32 v[40:41], v[20:21], v[94:95], v[40:41] op_sel:[0,1,0] op_sel_hi:[1,1,1]
	v_mul_f32_e32 v51, v100, v50
	v_add_f32_dpp v38, v38, v38 quad_perm:[1,0,3,2] row_mask:0xf bank_mask:0xf bound_ctrl:1
	v_add_f32_dpp v39, v39, v39 quad_perm:[1,0,3,2] row_mask:0xf bank_mask:0xf bound_ctrl:1
	v_add_f32_dpp v40, v40, v40 quad_perm:[1,0,3,2] row_mask:0xf bank_mask:0xf bound_ctrl:1
	v_add_f32_dpp v41, v41, v41 quad_perm:[1,0,3,2] row_mask:0xf bank_mask:0xf bound_ctrl:1
	v_add_f32_dpp v38, v38, v38 quad_perm:[2,3,0,1] row_mask:0xf bank_mask:0xf bound_ctrl:1
	v_add_f32_dpp v39, v39, v39 quad_perm:[2,3,0,1] row_mask:0xf bank_mask:0xf bound_ctrl:1
	v_add_f32_dpp v40, v40, v40 quad_perm:[2,3,0,1] row_mask:0xf bank_mask:0xf bound_ctrl:1
	v_add_f32_dpp v41, v41, v41 quad_perm:[2,3,0,1] row_mask:0xf bank_mask:0xf bound_ctrl:1
	v_add_f32_dpp v38, v38, v38 row_half_mirror row_mask:0xf bank_mask:0xf bound_ctrl:1
	v_add_f32_dpp v39, v39, v39 row_half_mirror row_mask:0xf bank_mask:0xf bound_ctrl:1
	v_add_f32_dpp v40, v40, v40 row_half_mirror row_mask:0xf bank_mask:0xf bound_ctrl:1
	v_add_f32_dpp v41, v41, v41 row_half_mirror row_mask:0xf bank_mask:0xf bound_ctrl:1
	v_add_f32_dpp v38, v38, v38 row_mirror row_mask:0xf bank_mask:0xf bound_ctrl:1
	v_add_f32_dpp v39, v39, v39 row_mirror row_mask:0xf bank_mask:0xf bound_ctrl:1
	v_add_f32_dpp v40, v40, v40 row_mirror row_mask:0xf bank_mask:0xf bound_ctrl:1
	v_add_f32_dpp v41, v41, v41 row_mirror row_mask:0xf bank_mask:0xf bound_ctrl:1
	v_cmp_gt_f32_e32 vcc, 0x2b8cbccc, v51
	v_pk_fma_f32 v[44:45], v[38:39], v[50:51], v[96:97] op_sel:[0,1,0] op_sel_hi:[1,1,1] neg_lo:[1,0,0] neg_hi:[1,0,0]
	v_pk_mul_f32 v[44:45], v[44:45], v[100:101] op_sel:[0,1] op_sel_hi:[1,1]
	v_pk_mul_f32 v[48:49], v[44:45], v[102:103] op_sel_hi:[1,0]
	v_pk_fma_f32 v[48:49], v[40:41], v[50:51], v[48:49] op_sel:[0,1,0] op_sel_hi:[1,1,1]
	s_cbranch_vccnz .Lgd2_rare1
.Lgd2_back1:
	v_rcp_f32_e32 v52, v51
	v_cvt_pk_bf16_f32 v54, v48, v49
	v_pk_mul_f32 v[46:47], v[44:45], v[52:53] op_sel_hi:[1,0]
	v_pk_fma_f32 v[6:7], v[80:81], v[46:47], v[6:7] op_sel_hi:[0,1,1]
	v_pk_fma_f32 v[8:9], v[82:83], v[46:47], v[8:9] op_sel_hi:[0,1,1]
	v_pk_fma_f32 v[10:11], v[84:85], v[46:47], v[10:11] op_sel_hi:[0,1,1]
	v_pk_fma_f32 v[12:13], v[86:87], v[46:47], v[12:13] op_sel_hi:[0,1,1]
	v_pk_fma_f32 v[14:15], v[88:89], v[46:47], v[14:15] op_sel_hi:[0,1,1]
	v_pk_fma_f32 v[16:17], v[90:91], v[46:47], v[16:17] op_sel_hi:[0,1,1]
	v_pk_fma_f32 v[18:19], v[92:93], v[46:47], v[18:19] op_sel_hi:[0,1,1]
	v_pk_fma_f32 v[20:21], v[94:95], v[46:47], v[20:21] op_sel_hi:[0,1,1]
	global_store_dword v154, v54, s[14:15]
	s_add_u32 s14, s14, 0x1000
	s_addc_u32 s15, s15, 0
	ds_read_b128 v[80:83], v22 offset:3072
	ds_read_b128 v[84:87], v22 offset:3328
	ds_read_b128 v[88:91], v22 offset:3584
	ds_read_b128 v[92:95], v22 offset:3840
	ds_read_b64 v[96:97], v23 offset:13056
	ds_read_b128 v[100:103], v24 offset:14384
	s_waitcnt lgkmcnt(6)
	v_pk_mul_f32 v[38:39], v[6:7], v[56:57] op_sel_hi:[1,0]
	v_pk_mul_f32 v[40:41], v[6:7], v[56:57] op_sel:[0,1] op_sel_hi:[1,1]
	v_pk_fma_f32 v[38:39], v[8:9], v[58:59], v[38:39] op_sel_hi:[1,0,1]
	v_pk_fma_f32 v[40:41], v[8:9], v[58:59], v[40:41] op_sel:[0,1,0] op_sel_hi:[1,1,1]
	v_pk_fma_f32 v[38:39], v[10:11], v[60:61], v[38:39] op_sel_hi:[1,0,1]
	v_pk_fma_f32 v[40:41], v[10:11], v[60:61], v[40:41] op_sel:[0,1,0] op_sel_hi:[1,1,1]
	v_pk_fma_f32 v[38:39], v[12:13], v[62:63], v[38:39] op_sel_hi:[1,0,1]
	v_pk_fma_f32 v[40:41], v[12:13], v[62:63], v[40:41] op_sel:[0,1,0] op_sel_hi:[1,1,1]
	v_pk_fma_f32 v[38:39], v[14:15], v[64:65], v[38:39] op_sel_hi:[1,0,1]
	v_pk_fma_f32 v[40:41], v[14:15], v[64:65], v[40:41] op_sel:[0,1,0] op_sel_hi:[1,1,1]
	v_pk_fma_f32 v[38:39], v[16:17], v[66:67], v[38:39] op_sel_hi:[1,0,1]
	v_pk_fma_f32 v[40:41], v[16:17], v[66:67], v[40:41] op_sel:[0,1,0] op_sel_hi:[1,1,1]
	v_pk_fma_f32 v[38:39], v[18:19], v[68:69], v[38:39] op_sel_hi:[1,0,1]
	v_pk_fma_f32 v[40:41], v[18:19], v[68:69], v[40:41] op_sel:[0,1,0] op_sel_hi:[1,1,1]
	v_pk_fma_f32 v[38:39], v[20:21], v[70:71], v[38:39] op_sel_hi:[1,0,1]
	v_pk_fma_f32 v[40:41], v[20:21], v[70:71], v[40:41] op_sel:[0,1,0] op_sel_hi:[1,1,1]
	v_mul_f32_e32 v50, v76, v51
	v_add_f32_dpp v38, v38, v38 quad_perm:[1,0,3,2] row_mask:0xf bank_mask:0xf bound_ctrl:1
	v_add_f32_dpp v39, v39, v39 quad_perm:[1,0,3,2] row_mask:0xf bank_mask:0xf bound_ctrl:1
	v_add_f32_dpp v40, v40, v40 quad_perm:[1,0,3,2] row_mask:0xf bank_mask:0xf bound_ctrl:1
	v_add_f32_dpp v41, v41, v41 quad_perm:[1,0,3,2] row_mask:0xf bank_mask:0xf bound_ctrl:1
	v_add_f32_dpp v38, v38, v38 quad_perm:[2,3,0,1] row_mask:0xf bank_mask:0xf bound_ctrl:1
	v_add_f32_dpp v39, v39, v39 quad_perm:[2,3,0,1] row_mask:0xf bank_mask:0xf bound_ctrl:1
	v_add_f32_dpp v40, v40, v40 quad_perm:[2,3,0,1] row_mask:0xf bank_mask:0xf bound_ctrl:1
	v_add_f32_dpp v41, v41, v41 quad_perm:[2,3,0,1] row_mask:0xf bank_mask:0xf bound_ctrl:1
	v_add_f32_dpp v38, v38, v38 row_half_mirror row_mask:0xf bank_mask:0xf bound_ctrl:1
	v_add_f32_dpp v39, v39, v39 row_half_mirror row_mask:0xf bank_mask:0xf bound_ctrl:1
	v_add_f32_dpp v40, v40, v40 row_half_mirror row_mask:0xf bank_mask:0xf bound_ctrl:1
	v_add_f32_dpp v41, v41, v41 row_half_mirror row_mask:0xf bank_mask:0xf bound_ctrl:1
	v_add_f32_dpp v38, v38, v38 row_mirror row_mask:0xf bank_mask:0xf bound_ctrl:1
	v_add_f32_dpp v39, v39, v39 row_mirror row_mask:0xf bank_mask:0xf bound_ctrl:1
	v_add_f32_dpp v40, v40, v40 row_mirror row_mask:0xf bank_mask:0xf bound_ctrl:1
	v_add_f32_dpp v41, v41, v41 row_mirror row_mask:0xf bank_mask:0xf bound_ctrl:1
	v_cmp_gt_f32_e32 vcc, 0x2b8cbccc, v50
	v_pk_fma_f32 v[44:45], v[38:39], v[50:51], v[72:73] op_sel:[0,0,0] op_sel_hi:[1,0,1] neg_lo:[1,0,0] neg_hi:[1,0,0]
	v_pk_mul_f32 v[44:45], v[44:45], v[76:77] op_sel:[0,1] op_sel_hi:[1,1]
	v_pk_mul_f32 v[48:49], v[44:45], v[78:79] op_sel_hi:[1,0]
	v_pk_fma_f32 v[48:49], v[40:41], v[50:51], v[48:49] op_sel:[0,0,0] op_sel_hi:[1,0,1]
	s_cbranch_vccnz .Lgd2_rare2
.Lgd2_back2:
	v_rcp_f32_e32 v52, v50
	v_cvt_pk_bf16_f32 v54, v48, v49
	v_pk_mul_f32 v[46:47], v[44:45], v[52:53] op_sel_hi:[1,0]
	v_pk_fma_f32 v[6:7], v[56:57], v[46:47], v[6:7] op_sel_hi:[0,1,1]
	v_pk_fma_f32 v[8:9], v[58:59], v[46:47], v[8:9] op_sel_hi:[0,1,1]
	v_pk_fma_f32 v[10:11], v[60:61], v[46:47], v[10:11] op_sel_hi:[0,1,1]
	v_pk_fma_f32 v[12:13], v[62:63], v[46:47], v[12:13] op_sel_hi:[0,1,1]
	v_pk_fma_f32 v[14:15], v[64:65], v[46:47], v[14:15] op_sel_hi:[0,1,1]
	v_pk_fma_f32 v[16:17], v[66:67], v[46:47], v[16:17] op_sel_hi:[0,1,1]
	v_pk_fma_f32 v[18:19], v[68:69], v[46:47], v[18:19] op_sel_hi:[0,1,1]
	v_pk_fma_f32 v[20:21], v[70:71], v[46:47], v[20:21] op_sel_hi:[0,1,1]
	global_store_dword v154, v54, s[14:15]
	s_add_u32 s14, s14, 0x1000
	s_addc_u32 s15, s15, 0
	ds_read_b128 v[56:59], v22 offset:4096
	ds_read_b128 v[60:63], v22 offset:4352
	ds_read_b128 v[64:67], v22 offset:4608
	ds_read_b128 v[68:71], v22 offset:4864
	ds_read_b64 v[72:73], v23 offset:13312
	ds_read_b128 v[76:79], v24 offset:14400
	s_waitcnt lgkmcnt(6)
	v_pk_mul_f32 v[38:39], v[6:7], v[80:81] op_sel_hi:[1,0]
	v_pk_mul_f32 v[40:41], v[6:7], v[80:81] op_sel:[0,1] op_sel_hi:[1,1]
	v_pk_fma_f32 v[38:39], v[8:9], v[82:83], v[38:39] op_sel_hi:[1,0,1]
	v_pk_fma_f32 v[40:41], v[8:9], v[82:83], v[40:41] op_sel:[0,1,0] op_sel_hi:[1,1,1]
	v_pk_fma_f32 v[38:39], v[10:11], v[84:85], v[38:39] op_sel_hi:[1,0,1]
	v_pk_fma_f32 v[40:41], v[10:11], v[84:85], v[40:41] op_sel:[0,1,0] op_sel_hi:[1,1,1]
	v_pk_fma_f32 v[38:39], v[12:13], v[86:87], v[38:39] op_sel_hi:[1,0,1]
	v_pk_fma_f32 v[40:41], v[12:13], v[86:87], v[40:41] op_sel:[0,1,0] op_sel_hi:[1,1,1]
	v_pk_fma_f32 v[38:39], v[14:15], v[88:89], v[38:39] op_sel_hi:[1,0,1]
	v_pk_fma_f32 v[40:41], v[14:15], v[88:89], v[40:41] op_sel:[0,1,0] op_sel_hi:[1,1,1]
	v_pk_fma_f32 v[38:39], v[16:17], v[90:91], v[38:39] op_sel_hi:[1,0,1]
	v_pk_fma_f32 v[40:41], v[16:17], v[90:91], v[40:41] op_sel:[0,1,0] op_sel_hi:[1,1,1]
	v_pk_fma_f32 v[38:39], v[18:19], v[92:93], v[38:39] op_sel_hi:[1,0,1]
	v_pk_fma_f32 v[40:41], v[18:19], v[92:93], v[40:41] op_sel:[0,1,0] op_sel_hi:[1,1,1]
	v_pk_fma_f32 v[38:39], v[20:21], v[94:95], v[38:39] op_sel_hi:[1,0,1]
	v_pk_fma_f32 v[40:41], v[20:21], v[94:95], v[40:41] op_sel:[0,1,0] op_sel_hi:[1,1,1]
	v_mul_f32_e32 v51, v100, v50
	v_add_f32_dpp v38, v38, v38 quad_perm:[1,0,3,2] row_mask:0xf bank_mask:0xf bound_ctrl:1
	v_add_f32_dpp v39, v39, v39 quad_perm:[1,0,3,2] row_mask:0xf bank_mask:0xf bound_ctrl:1
	v_add_f32_dpp v40, v40, v40 quad_perm:[1,0,3,2] row_mask:0xf bank_mask:0xf bound_ctrl:1
	v_add_f32_dpp v41, v41, v41 quad_perm:[1,0,3,2] row_mask:0xf bank_mask:0xf bound_ctrl:1
	v_add_f32_dpp v38, v38, v38 quad_perm:[2,3,0,1] row_mask:0xf bank_mask:0xf bound_ctrl:1
	v_add_f32_dpp v39, v39, v39 quad_perm:[2,3,0,1] row_mask:0xf bank_mask:0xf bound_ctrl:1
	v_add_f32_dpp v40, v40, v40 quad_perm:[2,3,0,1] row_mask:0xf bank_mask:0xf bound_ctrl:1
	v_add_f32_dpp v41, v41, v41 quad_perm:[2,3,0,1] row_mask:0xf bank_mask:0xf bound_ctrl:1
	v_add_f32_dpp v38, v38, v38 row_half_mirror row_mask:0xf bank_mask:0xf bound_ctrl:1
	v_add_f32_dpp v39, v39, v39 row_half_mirror row_mask:0xf bank_mask:0xf bound_ctrl:1
	v_add_f32_dpp v40, v40, v40 row_half_mirror row_mask:0xf bank_mask:0xf bound_ctrl:1
	v_add_f32_dpp v41, v41, v41 row_half_mirror row_mask:0xf bank_mask:0xf bound_ctrl:1
	v_add_f32_dpp v38, v38, v38 row_mirror row_mask:0xf bank_mask:0xf bound_ctrl:1
	v_add_f32_dpp v39, v39, v39 row_mirror row_mask:0xf bank_mask:0xf bound_ctrl:1
	v_add_f32_dpp v40, v40, v40 row_mirror row_mask:0xf bank_mask:0xf bound_ctrl:1
	v_add_f32_dpp v41, v41, v41 row_mirror row_mask:0xf bank_mask:0xf bound_ctrl:1
	v_cmp_gt_f32_e32 vcc, 0x2b8cbccc, v51
	v_pk_fma_f32 v[44:45], v[38:39], v[50:51], v[96:97] op_sel:[0,1,0] op_sel_hi:[1,1,1] neg_lo:[1,0,0] neg_hi:[1,0,0]
	v_pk_mul_f32 v[44:45], v[44:45], v[100:101] op_sel:[0,1] op_sel_hi:[1,1]
	v_pk_mul_f32 v[48:49], v[44:45], v[102:103] op_sel_hi:[1,0]
	v_pk_fma_f32 v[48:49], v[40:41], v[50:51], v[48:49] op_sel:[0,1,0] op_sel_hi:[1,1,1]
	s_cbranch_vccnz .Lgd2_rare3
.Lgd2_back3:
	v_rcp_f32_e32 v52, v51
	v_cvt_pk_bf16_f32 v54, v48, v49
	v_pk_mul_f32 v[46:47], v[44:45], v[52:53] op_sel_hi:[1,0]
	v_pk_fma_f32 v[6:7], v[80:81], v[46:47], v[6:7] op_sel_hi:[0,1,1]
	v_pk_fma_f32 v[8:9], v[82:83], v[46:47], v[8:9] op_sel_hi:[0,1,1]
	v_pk_fma_f32 v[10:11], v[84:85], v[46:47], v[10:11] op_sel_hi:[0,1,1]
	v_pk_fma_f32 v[12:13], v[86:87], v[46:47], v[12:13] op_sel_hi:[0,1,1]
	v_pk_fma_f32 v[14:15], v[88:89], v[46:47], v[14:15] op_sel_hi:[0,1,1]
	v_pk_fma_f32 v[16:17], v[90:91], v[46:47], v[16:17] op_sel_hi:[0,1,1]
	v_pk_fma_f32 v[18:19], v[92:93], v[46:47], v[18:19] op_sel_hi:[0,1,1]
	v_pk_fma_f32 v[20:21], v[94:95], v[46:47], v[20:21] op_sel_hi:[0,1,1]
	global_store_dword v154, v54, s[14:15]
	s_add_u32 s14, s14, 0x1000
	s_addc_u32 s15, s15, 0
	ds_read_b128 v[80:83], v22 offset:5120
	ds_read_b128 v[84:87], v22 offset:5376
	ds_read_b128 v[88:91], v22 offset:5632
	ds_read_b128 v[92:95], v22 offset:5888
	ds_read_b64 v[96:97], v23 offset:13568
	ds_read_b128 v[100:103], v24 offset:14416
	s_waitcnt lgkmcnt(6)
	v_pk_mul_f32 v[38:39], v[6:7], v[56:57] op_sel_hi:[1,0]
	v_pk_mul_f32 v[40:41], v[6:7], v[56:57] op_sel:[0,1] op_sel_hi:[1,1]
	v_pk_fma_f32 v[38:39], v[8:9], v[58:59], v[38:39] op_sel_hi:[1,0,1]
	v_pk_fma_f32 v[40:41], v[8:9], v[58:59], v[40:41] op_sel:[0,1,0] op_sel_hi:[1,1,1]
	v_pk_fma_f32 v[38:39], v[10:11], v[60:61], v[38:39] op_sel_hi:[1,0,1]
	v_pk_fma_f32 v[40:41], v[10:11], v[60:61], v[40:41] op_sel:[0,1,0] op_sel_hi:[1,1,1]
	v_pk_fma_f32 v[38:39], v[12:13], v[62:63], v[38:39] op_sel_hi:[1,0,1]
	v_pk_fma_f32 v[40:41], v[12:13], v[62:63], v[40:41] op_sel:[0,1,0] op_sel_hi:[1,1,1]
	v_pk_fma_f32 v[38:39], v[14:15], v[64:65], v[38:39] op_sel_hi:[1,0,1]
	v_pk_fma_f32 v[40:41], v[14:15], v[64:65], v[40:41] op_sel:[0,1,0] op_sel_hi:[1,1,1]
	v_pk_fma_f32 v[38:39], v[16:17], v[66:67], v[38:39] op_sel_hi:[1,0,1]
	v_pk_fma_f32 v[40:41], v[16:17], v[66:67], v[40:41] op_sel:[0,1,0] op_sel_hi:[1,1,1]
	v_pk_fma_f32 v[38:39], v[18:19], v[68:69], v[38:39] op_sel_hi:[1,0,1]
	v_pk_fma_f32 v[40:41], v[18:19], v[68:69], v[40:41] op_sel:[0,1,0] op_sel_hi:[1,1,1]
	v_pk_fma_f32 v[38:39], v[20:21], v[70:71], v[38:39] op_sel_hi:[1,0,1]
	v_pk_fma_f32 v[40:41], v[20:21], v[70:71], v[40:41] op_sel:[0,1,0] op_sel_hi:[1,1,1]
	v_mul_f32_e32 v50, v76, v51
	v_add_f32_dpp v38, v38, v38 quad_perm:[1,0,3,2] row_mask:0xf bank_mask:0xf bound_ctrl:1
	v_add_f32_dpp v39, v39, v39 quad_perm:[1,0,3,2] row_mask:0xf bank_mask:0xf bound_ctrl:1
	v_add_f32_dpp v40, v40, v40 quad_perm:[1,0,3,2] row_mask:0xf bank_mask:0xf bound_ctrl:1
	v_add_f32_dpp v41, v41, v41 quad_perm:[1,0,3,2] row_mask:0xf bank_mask:0xf bound_ctrl:1
	v_add_f32_dpp v38, v38, v38 quad_perm:[2,3,0,1] row_mask:0xf bank_mask:0xf bound_ctrl:1
	v_add_f32_dpp v39, v39, v39 quad_perm:[2,3,0,1] row_mask:0xf bank_mask:0xf bound_ctrl:1
	v_add_f32_dpp v40, v40, v40 quad_perm:[2,3,0,1] row_mask:0xf bank_mask:0xf bound_ctrl:1
	v_add_f32_dpp v41, v41, v41 quad_perm:[2,3,0,1] row_mask:0xf bank_mask:0xf bound_ctrl:1
	v_add_f32_dpp v38, v38, v38 row_half_mirror row_mask:0xf bank_mask:0xf bound_ctrl:1
	v_add_f32_dpp v39, v39, v39 row_half_mirror row_mask:0xf bank_mask:0xf bound_ctrl:1
	v_add_f32_dpp v40, v40, v40 row_half_mirror row_mask:0xf bank_mask:0xf bound_ctrl:1
	v_add_f32_dpp v41, v41, v41 row_half_mirror row_mask:0xf bank_mask:0xf bound_ctrl:1
	v_add_f32_dpp v38, v38, v38 row_mirror row_mask:0xf bank_mask:0xf bound_ctrl:1
	v_add_f32_dpp v39, v39, v39 row_mirror row_mask:0xf bank_mask:0xf bound_ctrl:1
	v_add_f32_dpp v40, v40, v40 row_mirror row_mask:0xf bank_mask:0xf bound_ctrl:1
	v_add_f32_dpp v41, v41, v41 row_mirror row_mask:0xf bank_mask:0xf bound_ctrl:1
	v_cmp_gt_f32_e32 vcc, 0x2b8cbccc, v50
	v_pk_fma_f32 v[44:45], v[38:39], v[50:51], v[72:73] op_sel:[0,0,0] op_sel_hi:[1,0,1] neg_lo:[1,0,0] neg_hi:[1,0,0]
	v_pk_mul_f32 v[44:45], v[44:45], v[76:77] op_sel:[0,1] op_sel_hi:[1,1]
	v_pk_mul_f32 v[48:49], v[44:45], v[78:79] op_sel_hi:[1,0]
	v_pk_fma_f32 v[48:49], v[40:41], v[50:51], v[48:49] op_sel:[0,0,0] op_sel_hi:[1,0,1]
	s_cbranch_vccnz .Lgd2_rare4
.Lgd2_back4:
	v_rcp_f32_e32 v52, v50
	v_cvt_pk_bf16_f32 v54, v48, v49
	v_pk_mul_f32 v[46:47], v[44:45], v[52:53] op_sel_hi:[1,0]
	v_pk_fma_f32 v[6:7], v[56:57], v[46:47], v[6:7] op_sel_hi:[0,1,1]
	v_pk_fma_f32 v[8:9], v[58:59], v[46:47], v[8:9] op_sel_hi:[0,1,1]
	v_pk_fma_f32 v[10:11], v[60:61], v[46:47], v[10:11] op_sel_hi:[0,1,1]
	v_pk_fma_f32 v[12:13], v[62:63], v[46:47], v[12:13] op_sel_hi:[0,1,1]
	v_pk_fma_f32 v[14:15], v[64:65], v[46:47], v[14:15] op_sel_hi:[0,1,1]
	v_pk_fma_f32 v[16:17], v[66:67], v[46:47], v[16:17] op_sel_hi:[0,1,1]
	v_pk_fma_f32 v[18:19], v[68:69], v[46:47], v[18:19] op_sel_hi:[0,1,1]
	v_pk_fma_f32 v[20:21], v[70:71], v[46:47], v[20:21] op_sel_hi:[0,1,1]
	global_store_dword v154, v54, s[14:15]
	s_add_u32 s14, s14, 0x1000
	s_addc_u32 s15, s15, 0
	ds_read_b128 v[56:59], v22 offset:6144
	ds_read_b128 v[60:63], v22 offset:6400
	ds_read_b128 v[64:67], v22 offset:6656
	ds_read_b128 v[68:71], v22 offset:6912
	ds_read_b64 v[72:73], v23 offset:13824
	ds_read_b128 v[76:79], v24 offset:14432
	s_waitcnt lgkmcnt(6)
	v_pk_mul_f32 v[38:39], v[6:7], v[80:81] op_sel_hi:[1,0]
	v_pk_mul_f32 v[40:41], v[6:7], v[80:81] op_sel:[0,1] op_sel_hi:[1,1]
	v_pk_fma_f32 v[38:39], v[8:9], v[82:83], v[38:39] op_sel_hi:[1,0,1]
	v_pk_fma_f32 v[40:41], v[8:9], v[82:83], v[40:41] op_sel:[0,1,0] op_sel_hi:[1,1,1]
	v_pk_fma_f32 v[38:39], v[10:11], v[84:85], v[38:39] op_sel_hi:[1,0,1]
	v_pk_fma_f32 v[40:41], v[10:11], v[84:85], v[40:41] op_sel:[0,1,0] op_sel_hi:[1,1,1]
	v_pk_fma_f32 v[38:39], v[12:13], v[86:87], v[38:39] op_sel_hi:[1,0,1]
	v_pk_fma_f32 v[40:41], v[12:13], v[86:87], v[40:41] op_sel:[0,1,0] op_sel_hi:[1,1,1]
	v_pk_fma_f32 v[38:39], v[14:15], v[88:89], v[38:39] op_sel_hi:[1,0,1]
	v_pk_fma_f32 v[40:41], v[14:15], v[88:89], v[40:41] op_sel:[0,1,0] op_sel_hi:[1,1,1]
	v_pk_fma_f32 v[38:39], v[16:17], v[90:91], v[38:39] op_sel_hi:[1,0,1]
	v_pk_fma_f32 v[40:41], v[16:17], v[90:91], v[40:41] op_sel:[0,1,0] op_sel_hi:[1,1,1]
	v_pk_fma_f32 v[38:39], v[18:19], v[92:93], v[38:39] op_sel_hi:[1,0,1]
	v_pk_fma_f32 v[40:41], v[18:19], v[92:93], v[40:41] op_sel:[0,1,0] op_sel_hi:[1,1,1]
	v_pk_fma_f32 v[38:39], v[20:21], v[94:95], v[38:39] op_sel_hi:[1,0,1]
	v_pk_fma_f32 v[40:41], v[20:21], v[94:95], v[40:41] op_sel:[0,1,0] op_sel_hi:[1,1,1]
	v_mul_f32_e32 v51, v100, v50
	v_add_f32_dpp v38, v38, v38 quad_perm:[1,0,3,2] row_mask:0xf bank_mask:0xf bound_ctrl:1
	v_add_f32_dpp v39, v39, v39 quad_perm:[1,0,3,2] row_mask:0xf bank_mask:0xf bound_ctrl:1
	v_add_f32_dpp v40, v40, v40 quad_perm:[1,0,3,2] row_mask:0xf bank_mask:0xf bound_ctrl:1
	v_add_f32_dpp v41, v41, v41 quad_perm:[1,0,3,2] row_mask:0xf bank_mask:0xf bound_ctrl:1
	v_add_f32_dpp v38, v38, v38 quad_perm:[2,3,0,1] row_mask:0xf bank_mask:0xf bound_ctrl:1
	v_add_f32_dpp v39, v39, v39 quad_perm:[2,3,0,1] row_mask:0xf bank_mask:0xf bound_ctrl:1
	v_add_f32_dpp v40, v40, v40 quad_perm:[2,3,0,1] row_mask:0xf bank_mask:0xf bound_ctrl:1
	v_add_f32_dpp v41, v41, v41 quad_perm:[2,3,0,1] row_mask:0xf bank_mask:0xf bound_ctrl:1
	v_add_f32_dpp v38, v38, v38 row_half_mirror row_mask:0xf bank_mask:0xf bound_ctrl:1
	v_add_f32_dpp v39, v39, v39 row_half_mirror row_mask:0xf bank_mask:0xf bound_ctrl:1
	v_add_f32_dpp v40, v40, v40 row_half_mirror row_mask:0xf bank_mask:0xf bound_ctrl:1
	v_add_f32_dpp v41, v41, v41 row_half_mirror row_mask:0xf bank_mask:0xf bound_ctrl:1
	v_add_f32_dpp v38, v38, v38 row_mirror row_mask:0xf bank_mask:0xf bound_ctrl:1
	v_add_f32_dpp v39, v39, v39 row_mirror row_mask:0xf bank_mask:0xf bound_ctrl:1
	v_add_f32_dpp v40, v40, v40 row_mirror row_mask:0xf bank_mask:0xf bound_ctrl:1
	v_add_f32_dpp v41, v41, v41 row_mirror row_mask:0xf bank_mask:0xf bound_ctrl:1
	v_cmp_gt_f32_e32 vcc, 0x2b8cbccc, v51
	v_pk_fma_f32 v[44:45], v[38:39], v[50:51], v[96:97] op_sel:[0,1,0] op_sel_hi:[1,1,1] neg_lo:[1,0,0] neg_hi:[1,0,0]
	v_pk_mul_f32 v[44:45], v[44:45], v[100:101] op_sel:[0,1] op_sel_hi:[1,1]
	v_pk_mul_f32 v[48:49], v[44:45], v[102:103] op_sel_hi:[1,0]
	v_pk_fma_f32 v[48:49], v[40:41], v[50:51], v[48:49] op_sel:[0,1,0] op_sel_hi:[1,1,1]
	s_cbranch_vccnz .Lgd2_rare5
.Lgd2_back5:
	v_rcp_f32_e32 v52, v51
	v_cvt_pk_bf16_f32 v54, v48, v49
	v_pk_mul_f32 v[46:47], v[44:45], v[52:53] op_sel_hi:[1,0]
	v_pk_fma_f32 v[6:7], v[80:81], v[46:47], v[6:7] op_sel_hi:[0,1,1]
	v_pk_fma_f32 v[8:9], v[82:83], v[46:47], v[8:9] op_sel_hi:[0,1,1]
	v_pk_fma_f32 v[10:11], v[84:85], v[46:47], v[10:11] op_sel_hi:[0,1,1]
	v_pk_fma_f32 v[12:13], v[86:87], v[46:47], v[12:13] op_sel_hi:[0,1,1]
	v_pk_fma_f32 v[14:15], v[88:89], v[46:47], v[14:15] op_sel_hi:[0,1,1]
	v_pk_fma_f32 v[16:17], v[90:91], v[46:47], v[16:17] op_sel_hi:[0,1,1]
	v_pk_fma_f32 v[18:19], v[92:93], v[46:47], v[18:19] op_sel_hi:[0,1,1]
	v_pk_fma_f32 v[20:21], v[94:95], v[46:47], v[20:21] op_sel_hi:[0,1,1]
	global_store_dword v154, v54, s[14:15]
	s_add_u32 s14, s14, 0x1000
	s_addc_u32 s15, s15, 0
	ds_read_b128 v[80:83], v22 offset:7168
	ds_read_b128 v[84:87], v22 offset:7424
	ds_read_b128 v[88:91], v22 offset:7680
	ds_read_b128 v[92:95], v22 offset:7936
	ds_read_b64 v[96:97], v23 offset:14080
	ds_read_b128 v[100:103], v24 offset:14448
	s_waitcnt lgkmcnt(6)
	v_pk_mul_f32 v[38:39], v[6:7], v[56:57] op_sel_hi:[1,0]
	v_pk_mul_f32 v[40:41], v[6:7], v[56:57] op_sel:[0,1] op_sel_hi:[1,1]
	v_pk_fma_f32 v[38:39], v[8:9], v[58:59], v[38:39] op_sel_hi:[1,0,1]
	v_pk_fma_f32 v[40:41], v[8:9], v[58:59], v[40:41] op_sel:[0,1,0] op_sel_hi:[1,1,1]
	v_pk_fma_f32 v[38:39], v[10:11], v[60:61], v[38:39] op_sel_hi:[1,0,1]
	v_pk_fma_f32 v[40:41], v[10:11], v[60:61], v[40:41] op_sel:[0,1,0] op_sel_hi:[1,1,1]
	v_pk_fma_f32 v[38:39], v[12:13], v[62:63], v[38:39] op_sel_hi:[1,0,1]
	v_pk_fma_f32 v[40:41], v[12:13], v[62:63], v[40:41] op_sel:[0,1,0] op_sel_hi:[1,1,1]
	v_pk_fma_f32 v[38:39], v[14:15], v[64:65], v[38:39] op_sel_hi:[1,0,1]
	v_pk_fma_f32 v[40:41], v[14:15], v[64:65], v[40:41] op_sel:[0,1,0] op_sel_hi:[1,1,1]
	v_pk_fma_f32 v[38:39], v[16:17], v[66:67], v[38:39] op_sel_hi:[1,0,1]
	v_pk_fma_f32 v[40:41], v[16:17], v[66:67], v[40:41] op_sel:[0,1,0] op_sel_hi:[1,1,1]
	v_pk_fma_f32 v[38:39], v[18:19], v[68:69], v[38:39] op_sel_hi:[1,0,1]
	v_pk_fma_f32 v[40:41], v[18:19], v[68:69], v[40:41] op_sel:[0,1,0] op_sel_hi:[1,1,1]
	v_pk_fma_f32 v[38:39], v[20:21], v[70:71], v[38:39] op_sel_hi:[1,0,1]
	v_pk_fma_f32 v[40:41], v[20:21], v[70:71], v[40:41] op_sel:[0,1,0] op_sel_hi:[1,1,1]
	v_mul_f32_e32 v50, v76, v51
	v_add_f32_dpp v38, v38, v38 quad_perm:[1,0,3,2] row_mask:0xf bank_mask:0xf bound_ctrl:1
	v_add_f32_dpp v39, v39, v39 quad_perm:[1,0,3,2] row_mask:0xf bank_mask:0xf bound_ctrl:1
	v_add_f32_dpp v40, v40, v40 quad_perm:[1,0,3,2] row_mask:0xf bank_mask:0xf bound_ctrl:1
	v_add_f32_dpp v41, v41, v41 quad_perm:[1,0,3,2] row_mask:0xf bank_mask:0xf bound_ctrl:1
	v_add_f32_dpp v38, v38, v38 quad_perm:[2,3,0,1] row_mask:0xf bank_mask:0xf bound_ctrl:1
	v_add_f32_dpp v39, v39, v39 quad_perm:[2,3,0,1] row_mask:0xf bank_mask:0xf bound_ctrl:1
	v_add_f32_dpp v40, v40, v40 quad_perm:[2,3,0,1] row_mask:0xf bank_mask:0xf bound_ctrl:1
	v_add_f32_dpp v41, v41, v41 quad_perm:[2,3,0,1] row_mask:0xf bank_mask:0xf bound_ctrl:1
	v_add_f32_dpp v38, v38, v38 row_half_mirror row_mask:0xf bank_mask:0xf bound_ctrl:1
	v_add_f32_dpp v39, v39, v39 row_half_mirror row_mask:0xf bank_mask:0xf bound_ctrl:1
	v_add_f32_dpp v40, v40, v40 row_half_mirror row_mask:0xf bank_mask:0xf bound_ctrl:1
	v_add_f32_dpp v41, v41, v41 row_half_mirror row_mask:0xf bank_mask:0xf bound_ctrl:1
	v_add_f32_dpp v38, v38, v38 row_mirror row_mask:0xf bank_mask:0xf bound_ctrl:1
	v_add_f32_dpp v39, v39, v39 row_mirror row_mask:0xf bank_mask:0xf bound_ctrl:1
	v_add_f32_dpp v40, v40, v40 row_mirror row_mask:0xf bank_mask:0xf bound_ctrl:1
	v_add_f32_dpp v41, v41, v41 row_mirror row_mask:0xf bank_mask:0xf bound_ctrl:1
	v_cmp_gt_f32_e32 vcc, 0x2b8cbccc, v50
	v_pk_fma_f32 v[44:45], v[38:39], v[50:51], v[72:73] op_sel:[0,0,0] op_sel_hi:[1,0,1] neg_lo:[1,0,0] neg_hi:[1,0,0]
	v_pk_mul_f32 v[44:45], v[44:45], v[76:77] op_sel:[0,1] op_sel_hi:[1,1]
	v_pk_mul_f32 v[48:49], v[44:45], v[78:79] op_sel_hi:[1,0]
	v_pk_fma_f32 v[48:49], v[40:41], v[50:51], v[48:49] op_sel:[0,0,0] op_sel_hi:[1,0,1]
	s_cbranch_vccnz .Lgd2_rare6
.Lgd2_back6:
	v_rcp_f32_e32 v52, v50
	v_cvt_pk_bf16_f32 v54, v48, v49
	v_pk_mul_f32 v[46:47], v[44:45], v[52:53] op_sel_hi:[1,0]
	v_pk_fma_f32 v[6:7], v[56:57], v[46:47], v[6:7] op_sel_hi:[0,1,1]
	v_pk_fma_f32 v[8:9], v[58:59], v[46:47], v[8:9] op_sel_hi:[0,1,1]
	v_pk_fma_f32 v[10:11], v[60:61], v[46:47], v[10:11] op_sel_hi:[0,1,1]
	v_pk_fma_f32 v[12:13], v[62:63], v[46:47], v[12:13] op_sel_hi:[0,1,1]
	v_pk_fma_f32 v[14:15], v[64:65], v[46:47], v[14:15] op_sel_hi:[0,1,1]
	v_pk_fma_f32 v[16:17], v[66:67], v[46:47], v[16:17] op_sel_hi:[0,1,1]
	v_pk_fma_f32 v[18:19], v[68:69], v[46:47], v[18:19] op_sel_hi:[0,1,1]
	v_pk_fma_f32 v[20:21], v[70:71], v[46:47], v[20:21] op_sel_hi:[0,1,1]
	global_store_dword v154, v54, s[14:15]
	s_add_u32 s14, s14, 0x1000
	s_addc_u32 s15, s15, 0
	ds_read_b128 v[56:59], v25 offset:0
	ds_read_b128 v[60:63], v25 offset:256
	ds_read_b128 v[64:67], v25 offset:512
	ds_read_b128 v[68:71], v25 offset:768
	ds_read_b64 v[72:73], v26 offset:12288
	ds_read_b128 v[76:79], v27 offset:14336
	s_waitcnt lgkmcnt(6)
	v_pk_mul_f32 v[38:39], v[6:7], v[80:81] op_sel_hi:[1,0]
	v_pk_mul_f32 v[40:41], v[6:7], v[80:81] op_sel:[0,1] op_sel_hi:[1,1]
	v_pk_fma_f32 v[38:39], v[8:9], v[82:83], v[38:39] op_sel_hi:[1,0,1]
	v_pk_fma_f32 v[40:41], v[8:9], v[82:83], v[40:41] op_sel:[0,1,0] op_sel_hi:[1,1,1]
	v_pk_fma_f32 v[38:39], v[10:11], v[84:85], v[38:39] op_sel_hi:[1,0,1]
	v_pk_fma_f32 v[40:41], v[10:11], v[84:85], v[40:41] op_sel:[0,1,0] op_sel_hi:[1,1,1]
	v_pk_fma_f32 v[38:39], v[12:13], v[86:87], v[38:39] op_sel_hi:[1,0,1]
	v_pk_fma_f32 v[40:41], v[12:13], v[86:87], v[40:41] op_sel:[0,1,0] op_sel_hi:[1,1,1]
	v_pk_fma_f32 v[38:39], v[14:15], v[88:89], v[38:39] op_sel_hi:[1,0,1]
	v_pk_fma_f32 v[40:41], v[14:15], v[88:89], v[40:41] op_sel:[0,1,0] op_sel_hi:[1,1,1]
	v_pk_fma_f32 v[38:39], v[16:17], v[90:91], v[38:39] op_sel_hi:[1,0,1]
	v_pk_fma_f32 v[40:41], v[16:17], v[90:91], v[40:41] op_sel:[0,1,0] op_sel_hi:[1,1,1]
	v_pk_fma_f32 v[38:39], v[18:19], v[92:93], v[38:39] op_sel_hi:[1,0,1]
	v_pk_fma_f32 v[40:41], v[18:19], v[92:93], v[40:41] op_sel:[0,1,0] op_sel_hi:[1,1,1]
	v_pk_fma_f32 v[38:39], v[20:21], v[94:95], v[38:39] op_sel_hi:[1,0,1]
	v_pk_fma_f32 v[40:41], v[20:21], v[94:95], v[40:41] op_sel:[0,1,0] op_sel_hi:[1,1,1]
	v_mul_f32_e32 v51, v100, v50
	v_add_f32_dpp v38, v38, v38 quad_perm:[1,0,3,2] row_mask:0xf bank_mask:0xf bound_ctrl:1
	v_add_f32_dpp v39, v39, v39 quad_perm:[1,0,3,2] row_mask:0xf bank_mask:0xf bound_ctrl:1
	v_add_f32_dpp v40, v40, v40 quad_perm:[1,0,3,2] row_mask:0xf bank_mask:0xf bound_ctrl:1
	v_add_f32_dpp v41, v41, v41 quad_perm:[1,0,3,2] row_mask:0xf bank_mask:0xf bound_ctrl:1
	v_add_f32_dpp v38, v38, v38 quad_perm:[2,3,0,1] row_mask:0xf bank_mask:0xf bound_ctrl:1
	v_add_f32_dpp v39, v39, v39 quad_perm:[2,3,0,1] row_mask:0xf bank_mask:0xf bound_ctrl:1
	v_add_f32_dpp v40, v40, v40 quad_perm:[2,3,0,1] row_mask:0xf bank_mask:0xf bound_ctrl:1
	v_add_f32_dpp v41, v41, v41 quad_perm:[2,3,0,1] row_mask:0xf bank_mask:0xf bound_ctrl:1
	v_add_f32_dpp v38, v38, v38 row_half_mirror row_mask:0xf bank_mask:0xf bound_ctrl:1
	v_add_f32_dpp v39, v39, v39 row_half_mirror row_mask:0xf bank_mask:0xf bound_ctrl:1
	v_add_f32_dpp v40, v40, v40 row_half_mirror row_mask:0xf bank_mask:0xf bound_ctrl:1
	v_add_f32_dpp v41, v41, v41 row_half_mirror row_mask:0xf bank_mask:0xf bound_ctrl:1
	v_add_f32_dpp v38, v38, v38 row_mirror row_mask:0xf bank_mask:0xf bound_ctrl:1
	v_add_f32_dpp v39, v39, v39 row_mirror row_mask:0xf bank_mask:0xf bound_ctrl:1
	v_add_f32_dpp v40, v40, v40 row_mirror row_mask:0xf bank_mask:0xf bound_ctrl:1
	v_add_f32_dpp v41, v41, v41 row_mirror row_mask:0xf bank_mask:0xf bound_ctrl:1
	v_cmp_gt_f32_e32 vcc, 0x2b8cbccc, v51
	v_pk_fma_f32 v[44:45], v[38:39], v[50:51], v[96:97] op_sel:[0,1,0] op_sel_hi:[1,1,1] neg_lo:[1,0,0] neg_hi:[1,0,0]
	v_pk_mul_f32 v[44:45], v[44:45], v[100:101] op_sel:[0,1] op_sel_hi:[1,1]
	v_pk_mul_f32 v[48:49], v[44:45], v[102:103] op_sel_hi:[1,0]
	v_pk_fma_f32 v[48:49], v[40:41], v[50:51], v[48:49] op_sel:[0,1,0] op_sel_hi:[1,1,1]
	s_cbranch_vccnz .Lgd2_rare7
.Lgd2_back7:
	v_rcp_f32_e32 v52, v51
	v_cvt_pk_bf16_f32 v54, v48, v49
	v_pk_mul_f32 v[46:47], v[44:45], v[52:53] op_sel_hi:[1,0]
	v_pk_fma_f32 v[6:7], v[80:81], v[46:47], v[6:7] op_sel_hi:[0,1,1]
	v_pk_fma_f32 v[8:9], v[82:83], v[46:47], v[8:9] op_sel_hi:[0,1,1]
	v_pk_fma_f32 v[10:11], v[84:85], v[46:47], v[10:11] op_sel_hi:[0,1,1]
	v_pk_fma_f32 v[12:13], v[86:87], v[46:47], v[12:13] op_sel_hi:[0,1,1]
	v_pk_fma_f32 v[14:15], v[88:89], v[46:47], v[14:15] op_sel_hi:[0,1,1]
	v_pk_fma_f32 v[16:17], v[90:91], v[46:47], v[16:17] op_sel_hi:[0,1,1]
	v_pk_fma_f32 v[18:19], v[92:93], v[46:47], v[18:19] op_sel_hi:[0,1,1]
	v_pk_fma_f32 v[20:21], v[94:95], v[46:47], v[20:21] op_sel_hi:[0,1,1]
	global_store_dword v154, v54, s[14:15]
	s_add_u32 s14, s14, 0x1000
	s_addc_u32 s15, s15, 0
	s_waitcnt vmcnt(8)
	v_lshlrev_b32_e32 v116, 16, v108
	v_lshlrev_b32_e32 v117, 16, v109
	v_and_b32_e32 v118, s17, v108
	v_and_b32_e32 v119, s17, v109
	v_lshlrev_b32_e32 v120, 16, v110
	v_and_b32_e32 v121, s17, v110
	v_lshlrev_b32_e32 v122, 16, v111
	v_and_b32_e32 v123, s17, v111
	v_lshlrev_b32_e32 v124, 16, v112
	v_and_b32_e32 v125, s17, v112
	ds_write_b128 v28, v[116:119]
	ds_write_b64 v29, v[120:121]
	ds_write_b64 v30, v[122:123]
	ds_write_b64 v30, v[124:125] offset:128
	ds_write_b32 v31, v113
	s_mov_b32 s0, s18
	s_mov_b32 s18, s19
	s_mov_b32 s19, s20
	s_mov_b32 s20, s0
	v_mov_b32_e32 v22, v25
	v_mov_b32_e32 v23, v26
	v_mov_b32_e32 v24, v27
	v_add_u32_e32 v25, s19, v2
	v_add_u32_e32 v26, s19, v3
	v_mov_b32_e32 v27, s19
	v_add_u32_e32 v28, s20, v32
	v_add_u32_e32 v29, s20, v33
	v_add_u32_e32 v30, s20, v34
	v_add_u32_e32 v31, s20, v35
	s_add_i32 s16, s16, 8
	s_waitcnt lgkmcnt(0)
	s_barrier
	s_cmpk_lt_u32 s16, 0x800
	s_cbranch_scc1 .Lgd2_loop
	s_setprio 0
	s_lshr_b32 s2, s27, 4
	s_lshl_b32 s4, s2, 16
	s_add_u32 s4, s4, 0x4080000
	s_add_u32 s0, s24, s4
	s_addc_u32 s1, s25, 0
	v_pk_mul_f32 v[108:109], v[6:7], v[50:51] op_sel:[0,1] op_sel_hi:[1,1]
	global_store_dwordx2 v153, v[108:109], s[0:1] offset:0
	v_pk_mul_f32 v[110:111], v[8:9], v[50:51] op_sel:[0,1] op_sel_hi:[1,1]
	global_store_dwordx2 v153, v[110:111], s[0:1] offset:512
	v_pk_mul_f32 v[108:109], v[10:11], v[50:51] op_sel:[0,1] op_sel_hi:[1,1]
	global_store_dwordx2 v153, v[108:109], s[0:1] offset:1024
	v_pk_mul_f32 v[110:111], v[12:13], v[50:51] op_sel:[0,1] op_sel_hi:[1,1]
	global_store_dwordx2 v153, v[110:111], s[0:1] offset:1536
	v_pk_mul_f32 v[108:109], v[14:15], v[50:51] op_sel:[0,1] op_sel_hi:[1,1]
	global_store_dwordx2 v153, v[108:109], s[0:1] offset:2048
	v_pk_mul_f32 v[110:111], v[16:17], v[50:51] op_sel:[0,1] op_sel_hi:[1,1]
	global_store_dwordx2 v153, v[110:111], s[0:1] offset:2560
	v_pk_mul_f32 v[108:109], v[18:19], v[50:51] op_sel:[0,1] op_sel_hi:[1,1]
	global_store_dwordx2 v153, v[108:109], s[0:1] offset:3072
	v_pk_mul_f32 v[110:111], v[20:21], v[50:51] op_sel:[0,1] op_sel_hi:[1,1]
	global_store_dwordx2 v153, v[110:111], s[0:1] offset:3584
	s_add_i32 s27, s27, s28
	s_waitcnt vmcnt(0)
	s_cmpk_lt_i32 s27, 0x400
	s_cbranch_scc1 .Lgd2_item
	s_branch .LBB0_232
